# attention dv=128 units v4: queue of 128 real units per XCD (no skipped tickets), V-fragment prefetch depth 3, row max under the first PV MFMAs, independent row-sum accumulators, pipelined drain; resca
# speedup vs baseline: 1.0785x; 1.0255x over previous
.LBB0_728:
	s_or_b64 exec, exec, s[6:7]
	s_waitcnt vmcnt(0)
	v_readfirstlane_b32 s2, v1
	s_nop 1
	v_add_u32_e32 v0, s2, v0
	s_movk_i32 s2, 0x7f
	v_cmp_lt_u32_e32 vcc, s2, v0
	s_and_saveexec_b64 s[2:3], vcc
	s_xor_b64 s[6:7], exec, s[2:3]
	s_cbranch_execz .LBB0_764
	v_readlane_b32 s3, v254, 51
	s_add_i32 s2, s3, 64
	s_and_b32 s2, s2, 0x1c0
	s_lshl_b32 s2, s2, 2
	v_mov_b32_e32 v0, s2
	s_add_i32 s2, s3, 0x80
	s_and_b32 s2, s2, 0x1c0
	s_lshl_b32 s2, s2, 2
	global_load_dword v4, v0, s[82:83] sc1
	v_mov_b32_e32 v0, s2
	s_add_i32 s2, s3, 0xc0
	s_and_b32 s2, s2, 0x1c0
	s_lshl_b32 s2, s2, 2
	global_load_dword v6, v0, s[82:83] sc1
	v_mov_b32_e32 v0, s2
	s_xor_b32 s2, s3, 0x100
	s_lshl_b32 s2, s2, 2
	global_load_dword v5, v0, s[82:83] sc1
	v_mov_b32_e32 v0, s2
	s_add_i32 s2, s3, 0x140
	s_and_b32 s2, s2, 0x1c0
	s_lshl_b32 s2, s2, 2
	global_load_dword v3, v0, s[82:83] sc1
	v_mov_b32_e32 v0, s2
	s_add_i32 s2, s3, 0x180
	s_and_b32 s2, s2, 0x1c0
	s_lshl_b32 s2, s2, 2
	global_load_dword v2, v0, s[82:83] sc1
	v_mov_b32_e32 v0, s2
	s_add_i32 s2, s3, 0x1c0
	s_and_b32 s2, s2, 0x1c0
	s_lshl_b32 s2, s2, 2
	global_load_dword v1, v0, s[82:83] sc1
	v_mov_b32_e32 v0, s2
	global_load_dword v0, v0, s[82:83] sc1
	s_movk_i32 s2, 0x80
	s_waitcnt vmcnt(6)
	v_cmp_gt_u32_e32 vcc, s2, v4
	v_mov_b32_e32 v4, -1
	s_cbranch_vccz .LBB0_733
	s_mov_b64 s[8:9], exec
	v_readlane_b32 s2, v254, 50
	v_mbcnt_lo_u32_b32 v4, s8, 0
	s_add_i32 s2, s2, 1
	v_mbcnt_hi_u32_b32 v4, s9, v4
	s_and_b32 s2, s2, 7
	v_cmp_eq_u32_e32 vcc, 0, v4
	s_and_saveexec_b64 s[10:11], vcc
	s_cbranch_execz .LBB0_732
	s_lshl_b32 s3, s2, 8
	s_bcnt1_i32_b64 s8, s[8:9]
	v_mov_b32_e32 v7, s3
	v_mov_b32_e32 v8, s8
	global_atomic_add v7, v7, v8, s[82:83] sc0
.LBB0_732:
	s_or_b64 exec, exec, s[10:11]
	s_waitcnt vmcnt(0)
	v_readfirstlane_b32 s3, v7
	s_nop 1
	v_add_u32_e32 v4, s3, v4
	s_movk_i32 s3, 0x80
	v_lshl_add_u32 v7, s2, 8, v4
	v_cmp_gt_u32_e32 vcc, s3, v4
	s_nop 1
	v_cndmask_b32_e32 v4, -1, v7, vcc
.LBB0_733:
	v_cmp_gt_i32_e32 vcc, 0, v4
	s_and_saveexec_b64 s[8:9], vcc
	s_cbranch_execz .LBB0_738
	s_movk_i32 s2, 0x7f
	s_waitcnt vmcnt(5)
	v_cmp_lt_u32_e32 vcc, s2, v6
	v_mov_b32_e32 v4, -1
	s_cbranch_vccnz .LBB0_738
	s_mov_b64 s[10:11], exec
	v_readlane_b32 s2, v254, 50
	v_mbcnt_lo_u32_b32 v4, s10, 0
	s_add_i32 s2, s2, 2
	v_mbcnt_hi_u32_b32 v4, s11, v4
	s_and_b32 s2, s2, 7
	v_cmp_eq_u32_e32 vcc, 0, v4
	s_and_saveexec_b64 s[12:13], vcc
	s_cbranch_execz .LBB0_737
	s_lshl_b32 s3, s2, 8
	s_bcnt1_i32_b64 s10, s[10:11]
	v_mov_b32_e32 v6, s3
	v_mov_b32_e32 v7, s10
	global_atomic_add v6, v6, v7, s[82:83] sc0
.LBB0_737:
	s_or_b64 exec, exec, s[12:13]
	s_waitcnt vmcnt(0)
	v_readfirstlane_b32 s3, v6
	s_nop 1
	v_add_u32_e32 v4, s3, v4
	s_movk_i32 s3, 0x80
	v_lshl_add_u32 v6, s2, 8, v4
	v_cmp_gt_u32_e32 vcc, s3, v4
	s_nop 1
	v_cndmask_b32_e32 v4, -1, v6, vcc
.LBB0_738:
	s_or_b64 exec, exec, s[8:9]
	v_cmp_gt_i32_e32 vcc, 0, v4
	s_and_saveexec_b64 s[8:9], vcc
	s_cbranch_execz .LBB0_743
	s_movk_i32 s2, 0x7f
	s_waitcnt vmcnt(4)
	v_cmp_lt_u32_e32 vcc, s2, v5
	v_mov_b32_e32 v4, -1
	s_cbranch_vccnz .LBB0_743
	s_mov_b64 s[10:11], exec
	v_readlane_b32 s2, v254, 50
	v_mbcnt_lo_u32_b32 v4, s10, 0
	s_add_i32 s2, s2, 3
	v_mbcnt_hi_u32_b32 v4, s11, v4
	s_and_b32 s2, s2, 7
	v_cmp_eq_u32_e32 vcc, 0, v4
	s_and_saveexec_b64 s[12:13], vcc
	s_cbranch_execz .LBB0_742
	s_lshl_b32 s3, s2, 8
	s_bcnt1_i32_b64 s10, s[10:11]
	v_mov_b32_e32 v5, s3
	v_mov_b32_e32 v6, s10
	global_atomic_add v5, v5, v6, s[82:83] sc0
.LBB0_742:
	s_or_b64 exec, exec, s[12:13]
	s_waitcnt vmcnt(0)
	v_readfirstlane_b32 s3, v5
	s_nop 1
	v_add_u32_e32 v4, s3, v4
	s_movk_i32 s3, 0x80
	v_lshl_add_u32 v5, s2, 8, v4
	v_cmp_gt_u32_e32 vcc, s3, v4
	s_nop 1
	v_cndmask_b32_e32 v4, -1, v5, vcc
.LBB0_743:
	s_or_b64 exec, exec, s[8:9]
	v_cmp_gt_i32_e32 vcc, 0, v4
	s_and_saveexec_b64 s[8:9], vcc
	s_cbranch_execz .LBB0_748
	s_movk_i32 s2, 0x7f
	s_waitcnt vmcnt(3)
	v_cmp_lt_u32_e32 vcc, s2, v3
	v_mov_b32_e32 v4, -1
	s_cbranch_vccnz .LBB0_748
	s_mov_b64 s[12:13], exec
	v_mbcnt_lo_u32_b32 v3, s12, 0
	v_readlane_b32 s2, v255, 3
	v_mbcnt_hi_u32_b32 v3, s13, v3
	s_xor_b32 s2, s2, 4
	v_cmp_eq_u32_e32 vcc, 0, v3
	s_and_saveexec_b64 s[10:11], vcc
	s_cbranch_execz .LBB0_747
	s_lshl_b32 s3, s2, 8
	s_bcnt1_i32_b64 s12, s[12:13]
	v_mov_b32_e32 v4, s3
	v_mov_b32_e32 v5, s12
	global_atomic_add v4, v4, v5, s[82:83] sc0
.LBB0_747:
	s_or_b64 exec, exec, s[10:11]
	s_waitcnt vmcnt(0)
	v_readfirstlane_b32 s3, v4
	s_nop 1
	v_add_u32_e32 v3, s3, v3
	s_movk_i32 s3, 0x80
	v_lshl_add_u32 v4, s2, 8, v3
	v_cmp_gt_u32_e32 vcc, s3, v3
	s_nop 1
	v_cndmask_b32_e32 v4, -1, v4, vcc
.LBB0_748:
	s_or_b64 exec, exec, s[8:9]
	v_cmp_gt_i32_e32 vcc, 0, v4
	s_and_saveexec_b64 s[8:9], vcc
	s_cbranch_execz .LBB0_753
	s_movk_i32 s2, 0x7f
	s_waitcnt vmcnt(2)
	v_cmp_lt_u32_e32 vcc, s2, v2
	v_mov_b32_e32 v4, -1
	s_cbranch_vccnz .LBB0_753
	s_mov_b64 s[10:11], exec
	v_readlane_b32 s2, v254, 50
	v_mbcnt_lo_u32_b32 v2, s10, 0
	s_add_i32 s2, s2, 5
	v_mbcnt_hi_u32_b32 v2, s11, v2
	s_and_b32 s2, s2, 7
	v_cmp_eq_u32_e32 vcc, 0, v2
	s_and_saveexec_b64 s[12:13], vcc
	s_cbranch_execz .LBB0_752
	s_lshl_b32 s3, s2, 8
	s_bcnt1_i32_b64 s10, s[10:11]
	v_mov_b32_e32 v3, s3
	v_mov_b32_e32 v4, s10
	global_atomic_add v3, v3, v4, s[82:83] sc0
.LBB0_752:
	s_or_b64 exec, exec, s[12:13]
	s_waitcnt vmcnt(0)
	v_readfirstlane_b32 s3, v3
	s_nop 1
	v_add_u32_e32 v2, s3, v2
	s_movk_i32 s3, 0x80
	v_lshl_add_u32 v3, s2, 8, v2
	v_cmp_gt_u32_e32 vcc, s3, v2
	s_nop 1
	v_cndmask_b32_e32 v4, -1, v3, vcc
.LBB0_753:
	s_or_b64 exec, exec, s[8:9]
	v_cmp_gt_i32_e32 vcc, 0, v4
	s_and_saveexec_b64 s[8:9], vcc
	s_cbranch_execz .LBB0_758
	s_movk_i32 s2, 0x7f
	s_waitcnt vmcnt(1)
	v_cmp_lt_u32_e32 vcc, s2, v1
	v_mov_b32_e32 v4, -1
	s_cbranch_vccnz .LBB0_758
	s_mov_b64 s[10:11], exec
	v_readlane_b32 s2, v254, 50
	v_mbcnt_lo_u32_b32 v1, s10, 0
	s_add_i32 s2, s2, 6
	v_mbcnt_hi_u32_b32 v1, s11, v1
	s_and_b32 s2, s2, 7
	v_cmp_eq_u32_e32 vcc, 0, v1
	s_and_saveexec_b64 s[12:13], vcc
	s_cbranch_execz .LBB0_757
	s_lshl_b32 s3, s2, 8
	s_bcnt1_i32_b64 s10, s[10:11]
	v_mov_b32_e32 v2, s3
	v_mov_b32_e32 v3, s10
	global_atomic_add v2, v2, v3, s[82:83] sc0
.LBB0_757:
	s_or_b64 exec, exec, s[12:13]
	s_waitcnt vmcnt(0)
	v_readfirstlane_b32 s3, v2
	s_nop 1
	v_add_u32_e32 v1, s3, v1
	s_movk_i32 s3, 0x80
	v_lshl_add_u32 v2, s2, 8, v1
	v_cmp_gt_u32_e32 vcc, s3, v1
	s_nop 1
	v_cndmask_b32_e32 v4, -1, v2, vcc
.LBB0_758:
	s_or_b64 exec, exec, s[8:9]
	v_cmp_gt_i32_e32 vcc, 0, v4
	s_and_saveexec_b64 s[8:9], vcc
	s_cbranch_execz .LBB0_763
	s_movk_i32 s2, 0x7f
	s_waitcnt vmcnt(0)
	v_cmp_lt_u32_e32 vcc, s2, v0
	v_mov_b32_e32 v4, -1
	s_cbranch_vccnz .LBB0_763
	s_mov_b64 s[10:11], exec
	v_readlane_b32 s2, v254, 50
	v_mbcnt_lo_u32_b32 v0, s10, 0
	s_add_i32 s2, s2, -1
	v_mbcnt_hi_u32_b32 v0, s11, v0
	s_and_b32 s2, s2, 7
	v_cmp_eq_u32_e32 vcc, 0, v0
	s_and_saveexec_b64 s[12:13], vcc
	s_cbranch_execz .LBB0_762
	s_lshl_b32 s3, s2, 8
	s_bcnt1_i32_b64 s10, s[10:11]
	v_mov_b32_e32 v1, s3
	v_mov_b32_e32 v2, s10
	global_atomic_add v1, v1, v2, s[82:83] sc0
.LBB0_762:
	s_or_b64 exec, exec, s[12:13]
	s_waitcnt vmcnt(0)
	v_readfirstlane_b32 s3, v1
	s_nop 1
	v_add_u32_e32 v0, s3, v0
	s_movk_i32 s3, 0x80
	v_lshl_add_u32 v1, s2, 8, v0
	v_cmp_gt_u32_e32 vcc, s3, v0
	s_nop 1
	v_cndmask_b32_e32 v4, -1, v1, vcc

.LBB0_767:
	s_or_b64 exec, exec, s[4:5]
	s_add_i32 s3, 0, 0x20140
	v_mov_b32_e32 v0, s3
	s_waitcnt lgkmcnt(0)
	s_barrier
	ds_read_b32 v0, v0
	s_mov_b32 s11, 0
	s_waitcnt lgkmcnt(0)
	s_barrier
	v_readfirstlane_b32 s40, v0
	s_cmp_lt_i32 s40, 0
	s_cbranch_scc1 .LBB0_892
	s_add_u32 s34, s82, 0xb000000
	s_addc_u32 s35, s83, 0
	s_add_u32 s36, s82, 0x9000000
	s_addc_u32 s37, s83, 0
	s_add_u32 s38, s82, 0x16000000
	v_mov_b32_e32 v16, 0
	s_mov_b32 s20, 0xffff0000
	s_addc_u32 s39, s83, 0
	v_mov_b32_e32 v1, 0
	s_mov_b64 s[12:13], 0x10000
	v_mov_b32_e32 v17, v16
	v_mov_b32_e32 v18, v16
	v_mov_b32_e32 v19, v16
	v_mov_b32_e32 v20, v16
	v_mov_b32_e32 v21, v16
	v_mov_b32_e32 v22, v16
	v_mov_b32_e32 v23, v16
	v_mov_b32_e32 v24, v16
	v_mov_b32_e32 v25, v16
	v_mov_b32_e32 v26, v16
	v_mov_b32_e32 v27, v16
	v_mov_b32_e32 v28, v16
	v_mov_b32_e32 v29, v16
	v_mov_b32_e32 v30, v16
	v_mov_b32_e32 v31, v16
	s_mov_b64 s[14:15], 0x20000
	s_movk_i32 s41, 0x80
	s_mov_b64 s[16:17], 0x30000
	s_mov_b64 s[18:19], 0x50000
	s_mov_b32 s21, -1
	s_mov_b32 s42, 0x41400000
	s_mov_b64 s[22:23], 0x40000
	s_movk_i32 s43, 0x7f
	v_mov_b32_e32 v222, 0xff800000
	s_branch .LBB0_771

.LBB0_775:
	s_or_b64 exec, exec, s[4:5]
	s_and_b32 s60, s40, 0xff
	s_and_b32 s61, s60, 63
	s_lshr_b32 s61, s61, 2
	s_sub_u32 s61, 15, s61
	s_lshr_b32 s62, s60, 6
	s_lshl_b32 s62, s62, 2
	s_and_b32 s63, s60, 3
	s_add_u32 s64, s62, s63
	s_lshl_b32 s65, s44, 1
	s_lshl_b32 s45, s61, 2
	s_add_u32 s45, s45, 4
	s_sub_u32 s72, s45, 4
	v_lshrrev_b32_e32 v0, 6, v236
	s_nop 0
	v_readfirstlane_b32 s47, v0
	s_lshl_b32 s66, s64, 22
	s_lshr_b32 s67, s65, 1
	s_lshl_b32 s67, s67, 7
	s_add_u32 s48, s82, 0x9000000
	s_addc_u32 s49, s83, 0
	s_add_u32 s48, s48, s66
	s_addc_u32 s49, s49, 0
	s_add_u32 s48, s48, s67
	s_addc_u32 s49, s49, 0
	s_lshr_b32 s63, s65, 2
	s_lshl_b32 s63, s63, 8
	s_add_u32 s50, s82, 0xb000000
	s_addc_u32 s51, s83, 0
	s_add_u32 s50, s50, s66
	s_addc_u32 s51, s51, 0
	s_add_u32 s50, s50, s63
	s_addc_u32 s51, s51, 0
	s_lshl_b32 s63, s61, 8
	s_lshl_b32 s60, s47, 5
	s_add_u32 s63, s63, s60
	s_lshl_b32 s60, s63, 10
	s_add_u32 s54, s82, 0x7000000
	s_addc_u32 s55, s83, 0
	s_add_u32 s54, s54, s66
	s_addc_u32 s55, s55, 0
	s_add_u32 s54, s54, s60
	s_addc_u32 s55, s55, 0
	s_add_u32 s54, s54, s67
	s_addc_u32 s55, s55, 0
	s_lshl_b32 s60, s64, 12
	s_add_u32 s60, s60, s63
	s_lshl_b32 s60, s60, 11
	s_and_b32 s67, s65, 14
	s_lshl_b32 s67, s67, 7
	s_add_u32 s52, s82, 0x16000000
	s_addc_u32 s53, s83, 0
	s_add_u32 s52, s52, s60
	s_addc_u32 s53, s53, 0
	s_add_u32 s52, s52, s67
	s_addc_u32 s53, s53, 0
	v_and_b32_e32 v237, 63, v236
	v_lshrrev_b32_e32 v252, 5, v237
	v_and_b32_e32 v0, 31, v237
	s_lshl_b32 s60, s47, 4
	v_lshl_add_u32 v238, v237, 10, s60
	s_and_b32 s60, s47, 3
	s_lshl_b32 s60, s60, 14
	s_lshr_b32 s61, s47, 2
	s_lshl_b32 s61, s61, 6
	s_add_u32 s60, s60, s61
	v_lshrrev_b32_e32 v1, 2, v237
	v_lshlrev_b32_e32 v1, 10, v1
	v_and_b32_e32 v2, 3, v237
	v_lshl_or_b32 v1, v2, 4, v1
	v_add_u32_e32 v239, s60, v1
	v_lshlrev_b32_e32 v244, 10, v252
	v_lshl_or_b32 v244, v0, 4, v244
	v_bfe_u32 v1, v237, 4, 1
	v_lshlrev_b32_e32 v1, 5, v1
	v_lshl_or_b32 v1, v2, 3, v1
	v_bfe_u32 v2, v237, 2, 2
	v_lshl_or_b32 v2, v252, 2, v2
	v_lshl_or_b32 v1, v2, 6, v1
	v_add_u32_e32 v245, 24576, v1
	s_lshl_b32 s60, s47, 5
	v_add_u32_e32 v246, s60, v0
	s_lshl_b32 s60, s47, 8
	s_add_u32 s60, s60, 73728
	v_mov_b32_e32 v249, s60
	s_lshl_b32 s70, s47, 10
	s_add_u32 s71, s70, 24576
	s_mov_b64 s[74:75], s[48:49]
	s_mov_b64 s[76:77], s[50:51]
	s_mov_b32 s56, 0x4000
	s_mov_b32 s57, 0
	s_mov_b32 s58, 0x2000
	s_add_i32 m0, s57, s70
	s_nop 0
	global_load_lds_dwordx4 v238, s[74:75]
	s_add_u32 s74, s74, 0x10000
	s_addc_u32 s75, s75, 0
	s_lshl_b32 s60, s57, 1
	s_add_i32 s60, s60, s71
	s_mov_b32 m0, s60
	s_nop 0
	global_load_lds_dwordx4 v239, s[76:77]
	s_add_u32 s62, s76, 0x80
	s_addc_u32 s63, s77, 0
	s_add_i32 m0, s60, 0x2000
	s_nop 0
	global_load_lds_dwordx4 v239, s[62:63]
	s_add_u32 s76, s76, 0x10000
	s_addc_u32 s77, s77, 0
	s_add_i32 m0, s58, s70
	s_nop 0
	global_load_lds_dwordx4 v238, s[74:75]
	s_add_u32 s74, s74, 0x10000
	s_addc_u32 s75, s75, 0
	v_lshlrev_b32_e32 v1, 10, v0
	v_lshl_or_b32 v1, v252, 4, v1
	global_load_dwordx4 v[16:19], v1, s[54:55]
	global_load_dwordx4 v[20:23], v1, s[54:55] offset:32
	global_load_dwordx4 v[24:27], v1, s[54:55] offset:64
	global_load_dwordx4 v[28:31], v1, s[54:55] offset:96
	s_add_i32 m0, s56, s70
	s_nop 0
	global_load_lds_dwordx4 v238, s[74:75]
	s_add_u32 s74, s74, 0x10000
	s_addc_u32 s75, s75, 0
	v_mov_b32_e32 v248, 0
	v_mov_b32_e32 v247, 0
	v_mov_b32_e32 v160, 0
	v_mov_b32_e32 v161, 0
	v_mov_b32_e32 v162, 0
	v_mov_b32_e32 v163, 0
	v_mov_b32_e32 v164, 0
	v_mov_b32_e32 v165, 0
	v_mov_b32_e32 v166, 0
	v_mov_b32_e32 v167, 0
	v_mov_b32_e32 v168, 0
	v_mov_b32_e32 v169, 0
	v_mov_b32_e32 v170, 0
	v_mov_b32_e32 v171, 0
	v_mov_b32_e32 v172, 0
	v_mov_b32_e32 v173, 0
	v_mov_b32_e32 v174, 0
	v_mov_b32_e32 v175, 0
	v_mov_b32_e32 v32, 0
	v_mov_b32_e32 v33, 0
	v_mov_b32_e32 v34, 0
	v_mov_b32_e32 v35, 0
	v_mov_b32_e32 v36, 0
	v_mov_b32_e32 v37, 0
	v_mov_b32_e32 v38, 0
	v_mov_b32_e32 v39, 0
	v_mov_b32_e32 v40, 0
	v_mov_b32_e32 v41, 0
	v_mov_b32_e32 v42, 0
	v_mov_b32_e32 v43, 0
	v_mov_b32_e32 v44, 0
	v_mov_b32_e32 v45, 0
	v_mov_b32_e32 v46, 0
	v_mov_b32_e32 v47, 0
	v_mov_b32_e32 v48, 0
	v_mov_b32_e32 v49, 0
	v_mov_b32_e32 v50, 0
	v_mov_b32_e32 v51, 0
	v_mov_b32_e32 v52, 0
	v_mov_b32_e32 v53, 0
	v_mov_b32_e32 v54, 0
	v_mov_b32_e32 v55, 0
	v_mov_b32_e32 v56, 0
	v_mov_b32_e32 v57, 0
	v_mov_b32_e32 v58, 0
	v_mov_b32_e32 v59, 0
	v_mov_b32_e32 v60, 0
	v_mov_b32_e32 v61, 0
	v_mov_b32_e32 v62, 0
	v_mov_b32_e32 v63, 0
	v_mov_b32_e32 v64, 0
	v_mov_b32_e32 v65, 0
	v_mov_b32_e32 v66, 0
	v_mov_b32_e32 v67, 0
	v_mov_b32_e32 v68, 0
	v_mov_b32_e32 v69, 0
	v_mov_b32_e32 v70, 0
	v_mov_b32_e32 v71, 0
	v_mov_b32_e32 v72, 0
	v_mov_b32_e32 v73, 0
	v_mov_b32_e32 v74, 0
	v_mov_b32_e32 v75, 0
	v_mov_b32_e32 v76, 0
	v_mov_b32_e32 v77, 0
	v_mov_b32_e32 v78, 0
	v_mov_b32_e32 v79, 0
	v_mov_b32_e32 v80, 0
	v_mov_b32_e32 v81, 0
	v_mov_b32_e32 v82, 0
	v_mov_b32_e32 v83, 0
	v_mov_b32_e32 v84, 0
	v_mov_b32_e32 v85, 0
	v_mov_b32_e32 v86, 0
	v_mov_b32_e32 v87, 0
	v_mov_b32_e32 v88, 0
	v_mov_b32_e32 v89, 0
	v_mov_b32_e32 v90, 0
	v_mov_b32_e32 v91, 0
	v_mov_b32_e32 v92, 0
	v_mov_b32_e32 v93, 0
	v_mov_b32_e32 v94, 0
	v_mov_b32_e32 v95, 0
	s_mov_b32 s46, 0
	s_waitcnt vmcnt(8) lgkmcnt(0)
	s_barrier
	v_add_u32_e32 v250, s57, v244
	ds_read_b128 v[208:211], v250
	ds_read_b128 v[212:215], v250 offset:512
	ds_read_b128 v[216:219], v250 offset:2048
	ds_read_b128 v[220:223], v250 offset:2560
	ds_read_b128 v[224:227], v250 offset:4096
	ds_read_b128 v[228:231], v250 offset:4608
	ds_read_b128 v[232:235], v250 offset:6144
	ds_read_b128 v[240:243], v250 offset:6656
	s_waitcnt vmcnt(1) lgkmcnt(0)
	v_mfma_f32_32x32x16_bf16 v[96:111], v[208:211], v[16:19], v[160:175]
	v_mfma_f32_32x32x16_bf16 v[112:127], v[212:215], v[16:19], v[160:175]
	v_mfma_f32_32x32x16_bf16 v[96:111], v[216:219], v[20:23], v[96:111]
	v_mfma_f32_32x32x16_bf16 v[112:127], v[220:223], v[20:23], v[112:127]
	v_mfma_f32_32x32x16_bf16 v[96:111], v[224:227], v[24:27], v[96:111]
	v_mfma_f32_32x32x16_bf16 v[112:127], v[228:231], v[24:27], v[112:127]
	v_mfma_f32_32x32x16_bf16 v[96:111], v[232:235], v[28:31], v[96:111]
	v_mfma_f32_32x32x16_bf16 v[112:127], v[240:243], v[28:31], v[112:127]
	s_nop 7
	s_nop 7
	s_cmp_lt_u32 s46, s72
	s_cbranch_scc1 .Lat_nomask_230
	s_sub_u32 s60, s46, s72
	s_lshl_b32 s60, s60, 6
	v_lshl_add_u32 v0, v252, 2, s60
	v_sub_u32_e32 v0, v246, v0
	v_mov_b32_e32 v1, 0xff800000
	v_cmp_gt_i32_e64 s[60:61], 0, v0
	v_cmp_gt_i32_e64 s[62:63], 32, v0
	v_cmp_gt_i32_e64 s[64:65], 1, v0
	v_cmp_gt_i32_e64 s[66:67], 33, v0
	v_cndmask_b32_e64 v96, v96, v1, s[60:61]
	v_cmp_gt_i32_e64 s[60:61], 2, v0
	v_cndmask_b32_e64 v112, v112, v1, s[62:63]
	v_cmp_gt_i32_e64 s[62:63], 34, v0
	v_cndmask_b32_e64 v97, v97, v1, s[64:65]
	v_cmp_gt_i32_e64 s[64:65], 3, v0
	v_cndmask_b32_e64 v113, v113, v1, s[66:67]
	v_cmp_gt_i32_e64 s[66:67], 35, v0
	v_cndmask_b32_e64 v98, v98, v1, s[60:61]
	v_cmp_gt_i32_e64 s[60:61], 8, v0
	v_cndmask_b32_e64 v114, v114, v1, s[62:63]
	v_cmp_gt_i32_e64 s[62:63], 40, v0
	v_cndmask_b32_e64 v99, v99, v1, s[64:65]
	v_cmp_gt_i32_e64 s[64:65], 9, v0
	v_cndmask_b32_e64 v115, v115, v1, s[66:67]
	v_cmp_gt_i32_e64 s[66:67], 41, v0
	v_cndmask_b32_e64 v100, v100, v1, s[60:61]
	v_cmp_gt_i32_e64 s[60:61], 10, v0
	v_cndmask_b32_e64 v116, v116, v1, s[62:63]
	v_cmp_gt_i32_e64 s[62:63], 42, v0
	v_cndmask_b32_e64 v101, v101, v1, s[64:65]
	v_cmp_gt_i32_e64 s[64:65], 11, v0
	v_cndmask_b32_e64 v117, v117, v1, s[66:67]
	v_cmp_gt_i32_e64 s[66:67], 43, v0
	v_cndmask_b32_e64 v102, v102, v1, s[60:61]
	v_cmp_gt_i32_e64 s[60:61], 16, v0
	v_cndmask_b32_e64 v118, v118, v1, s[62:63]
	v_cmp_gt_i32_e64 s[62:63], 48, v0
	v_cndmask_b32_e64 v103, v103, v1, s[64:65]
	v_cmp_gt_i32_e64 s[64:65], 17, v0
	v_cndmask_b32_e64 v119, v119, v1, s[66:67]
	v_cmp_gt_i32_e64 s[66:67], 49, v0
	v_cndmask_b32_e64 v104, v104, v1, s[60:61]
	v_cmp_gt_i32_e64 s[60:61], 18, v0
	v_cndmask_b32_e64 v120, v120, v1, s[62:63]
	v_cmp_gt_i32_e64 s[62:63], 50, v0
	v_cndmask_b32_e64 v105, v105, v1, s[64:65]
	v_cmp_gt_i32_e64 s[64:65], 19, v0
	v_cndmask_b32_e64 v121, v121, v1, s[66:67]
	v_cmp_gt_i32_e64 s[66:67], 51, v0
	v_cndmask_b32_e64 v106, v106, v1, s[60:61]
	v_cmp_gt_i32_e64 s[60:61], 24, v0
	v_cndmask_b32_e64 v122, v122, v1, s[62:63]
	v_cmp_gt_i32_e64 s[62:63], 56, v0
	v_cndmask_b32_e64 v107, v107, v1, s[64:65]
	v_cmp_gt_i32_e64 s[64:65], 25, v0
	v_cndmask_b32_e64 v123, v123, v1, s[66:67]
	v_cmp_gt_i32_e64 s[66:67], 57, v0
	v_cndmask_b32_e64 v108, v108, v1, s[60:61]
	v_cmp_gt_i32_e64 s[60:61], 26, v0
	v_cndmask_b32_e64 v124, v124, v1, s[62:63]
	v_cmp_gt_i32_e64 s[62:63], 58, v0
	v_cndmask_b32_e64 v109, v109, v1, s[64:65]
	v_cmp_gt_i32_e64 s[64:65], 27, v0
	v_cndmask_b32_e64 v125, v125, v1, s[66:67]
	v_cmp_gt_i32_e64 s[66:67], 59, v0
	v_cndmask_b32_e64 v110, v110, v1, s[60:61]
	s_nop 1
	v_cndmask_b32_e64 v126, v126, v1, s[62:63]
	v_cndmask_b32_e64 v111, v111, v1, s[64:65]
	v_cndmask_b32_e64 v127, v127, v1, s[66:67]

.Lat_loop:
	s_cmp_ge_u32 s46, s45
	s_cbranch_scc1 .Lat_drain
	s_lshl_b32 s60, s56, 1
	v_add_u32_e32 v250, s60, v245
	v_mov_b32_e32 v8, 0
	v_mov_b32_e32 v9, 0
	v_mov_b32_e32 v10, 0
	v_mov_b32_e32 v11, 0
	v_mfma_f32_32x32x16_bf16 v[128:143], v[208:211], v[16:19], v[160:175]
	v_add_f32_e32 v8, v8, v96
	v_add_f32_e32 v9, v9, v97
	v_add_f32_e32 v10, v10, v98
	v_add_f32_e32 v11, v11, v99
	v_cvt_pk_bf16_f32 v176, v96, v97
	v_cvt_pk_bf16_f32 v177, v98, v99
	v_mfma_f32_32x32x16_bf16 v[144:159], v[212:215], v[16:19], v[160:175]
	v_add_f32_e32 v8, v8, v100
	v_add_f32_e32 v9, v9, v101
	v_add_f32_e32 v10, v10, v102
	v_add_f32_e32 v11, v11, v103
	v_cvt_pk_bf16_f32 v178, v100, v101
	v_cvt_pk_bf16_f32 v179, v102, v103
	v_mfma_f32_32x32x16_bf16 v[128:143], v[216:219], v[20:23], v[128:143]
	v_add_f32_e32 v8, v8, v104
	v_add_f32_e32 v9, v9, v105
	v_add_f32_e32 v10, v10, v106
	v_add_f32_e32 v11, v11, v107
	v_cvt_pk_bf16_f32 v180, v104, v105
	v_cvt_pk_bf16_f32 v181, v106, v107
	v_mfma_f32_32x32x16_bf16 v[144:159], v[220:223], v[20:23], v[144:159]
	v_add_f32_e32 v8, v8, v108
	v_add_f32_e32 v9, v9, v109
	v_add_f32_e32 v10, v10, v110
	v_add_f32_e32 v11, v11, v111
	v_cvt_pk_bf16_f32 v182, v108, v109
	v_cvt_pk_bf16_f32 v183, v110, v111
	v_mfma_f32_32x32x16_bf16 v[128:143], v[224:227], v[24:27], v[128:143]
	v_add_f32_e32 v8, v8, v112
	v_add_f32_e32 v9, v9, v113
	v_add_f32_e32 v10, v10, v114
	v_add_f32_e32 v11, v11, v115
	v_cvt_pk_bf16_f32 v184, v112, v113
	v_cvt_pk_bf16_f32 v185, v114, v115
	v_mfma_f32_32x32x16_bf16 v[144:159], v[228:231], v[24:27], v[144:159]
	v_add_f32_e32 v8, v8, v116
	v_add_f32_e32 v9, v9, v117
	v_add_f32_e32 v10, v10, v118
	v_add_f32_e32 v11, v11, v119
	v_cvt_pk_bf16_f32 v186, v116, v117
	v_cvt_pk_bf16_f32 v187, v118, v119
	ds_read_b64_tr_b16 v[192:193], v250 offset:0
	ds_read_b64_tr_b16 v[194:195], v250 offset:512
	v_mfma_f32_32x32x16_bf16 v[128:143], v[232:235], v[28:31], v[128:143]
	v_add_f32_e32 v8, v8, v120
	v_add_f32_e32 v9, v9, v121
	v_add_f32_e32 v10, v10, v122
	v_add_f32_e32 v11, v11, v123
	v_cvt_pk_bf16_f32 v188, v120, v121
	v_cvt_pk_bf16_f32 v189, v122, v123
	ds_read_b64_tr_b16 v[196:197], v250 offset:4096
	ds_read_b64_tr_b16 v[198:199], v250 offset:4608
	v_mfma_f32_32x32x16_bf16 v[144:159], v[240:243], v[28:31], v[144:159]
	v_add_f32_e32 v8, v8, v124
	v_add_f32_e32 v9, v9, v125
	v_add_f32_e32 v10, v10, v126
	v_add_f32_e32 v11, v11, v127
	v_cvt_pk_bf16_f32 v190, v124, v125
	v_cvt_pk_bf16_f32 v191, v126, v127
	ds_read_b64_tr_b16 v[200:201], v250 offset:8192
	ds_read_b64_tr_b16 v[202:203], v250 offset:8704
	v_add_f32_e32 v8, v8, v9
	v_add_f32_e32 v10, v10, v11
	v_add_f32_e32 v8, v8, v10
	v_add_f32_e32 v247, v247, v8
	s_add_i32 m0, s57, s70
	s_nop 0
	global_load_lds_dwordx4 v238, s[74:75]
	s_add_u32 s74, s74, 0x10000
	s_addc_u32 s75, s75, 0
	s_lshl_b32 s60, s58, 1
	s_add_i32 s60, s60, s71
	s_mov_b32 m0, s60
	s_nop 0
	global_load_lds_dwordx4 v239, s[76:77]
	s_add_u32 s62, s76, 0x80
	s_addc_u32 s63, s77, 0
	s_add_i32 m0, s60, 0x2000
	s_nop 0
	global_load_lds_dwordx4 v239, s[62:63]
	s_add_u32 s76, s76, 0x10000
	s_addc_u32 s77, s77, 0
	s_cmp_lt_u32 s46, s72
	s_cbranch_scc1 .Lat_nomask_534
	s_sub_u32 s60, s46, s72
	s_lshl_b32 s60, s60, 6
	v_lshl_add_u32 v0, v252, 2, s60
	v_sub_u32_e32 v0, v246, v0
	v_mov_b32_e32 v1, 0xff800000
	v_cmp_gt_i32_e64 s[60:61], 0, v0
	v_cmp_gt_i32_e64 s[62:63], 32, v0
	v_cmp_gt_i32_e64 s[64:65], 1, v0
	v_cmp_gt_i32_e64 s[66:67], 33, v0
	v_cndmask_b32_e64 v128, v128, v1, s[60:61]
	v_cmp_gt_i32_e64 s[60:61], 2, v0
	v_cndmask_b32_e64 v144, v144, v1, s[62:63]
	v_cmp_gt_i32_e64 s[62:63], 34, v0
	v_cndmask_b32_e64 v129, v129, v1, s[64:65]
	v_cmp_gt_i32_e64 s[64:65], 3, v0
	v_cndmask_b32_e64 v145, v145, v1, s[66:67]
	v_cmp_gt_i32_e64 s[66:67], 35, v0
	v_cndmask_b32_e64 v130, v130, v1, s[60:61]
	v_cmp_gt_i32_e64 s[60:61], 8, v0
	v_cndmask_b32_e64 v146, v146, v1, s[62:63]
	v_cmp_gt_i32_e64 s[62:63], 40, v0
	v_cndmask_b32_e64 v131, v131, v1, s[64:65]
	v_cmp_gt_i32_e64 s[64:65], 9, v0
	v_cndmask_b32_e64 v147, v147, v1, s[66:67]
	v_cmp_gt_i32_e64 s[66:67], 41, v0
	v_cndmask_b32_e64 v132, v132, v1, s[60:61]
	v_cmp_gt_i32_e64 s[60:61], 10, v0
	v_cndmask_b32_e64 v148, v148, v1, s[62:63]
	v_cmp_gt_i32_e64 s[62:63], 42, v0
	v_cndmask_b32_e64 v133, v133, v1, s[64:65]
	v_cmp_gt_i32_e64 s[64:65], 11, v0
	v_cndmask_b32_e64 v149, v149, v1, s[66:67]
	v_cmp_gt_i32_e64 s[66:67], 43, v0
	v_cndmask_b32_e64 v134, v134, v1, s[60:61]
	v_cmp_gt_i32_e64 s[60:61], 16, v0
	v_cndmask_b32_e64 v150, v150, v1, s[62:63]
	v_cmp_gt_i32_e64 s[62:63], 48, v0
	v_cndmask_b32_e64 v135, v135, v1, s[64:65]
	v_cmp_gt_i32_e64 s[64:65], 17, v0
	v_cndmask_b32_e64 v151, v151, v1, s[66:67]
	v_cmp_gt_i32_e64 s[66:67], 49, v0
	v_cndmask_b32_e64 v136, v136, v1, s[60:61]
	v_cmp_gt_i32_e64 s[60:61], 18, v0
	v_cndmask_b32_e64 v152, v152, v1, s[62:63]
	v_cmp_gt_i32_e64 s[62:63], 50, v0
	v_cndmask_b32_e64 v137, v137, v1, s[64:65]
	v_cmp_gt_i32_e64 s[64:65], 19, v0
	v_cndmask_b32_e64 v153, v153, v1, s[66:67]
	v_cmp_gt_i32_e64 s[66:67], 51, v0
	v_cndmask_b32_e64 v138, v138, v1, s[60:61]
	v_cmp_gt_i32_e64 s[60:61], 24, v0
	v_cndmask_b32_e64 v154, v154, v1, s[62:63]
	v_cmp_gt_i32_e64 s[62:63], 56, v0
	v_cndmask_b32_e64 v139, v139, v1, s[64:65]
	v_cmp_gt_i32_e64 s[64:65], 25, v0
	v_cndmask_b32_e64 v155, v155, v1, s[66:67]
	v_cmp_gt_i32_e64 s[66:67], 57, v0
	v_cndmask_b32_e64 v140, v140, v1, s[60:61]
	v_cmp_gt_i32_e64 s[60:61], 26, v0
	v_cndmask_b32_e64 v156, v156, v1, s[62:63]
	v_cmp_gt_i32_e64 s[62:63], 58, v0
	v_cndmask_b32_e64 v141, v141, v1, s[64:65]
	v_cmp_gt_i32_e64 s[64:65], 27, v0
	v_cndmask_b32_e64 v157, v157, v1, s[66:67]
	v_cmp_gt_i32_e64 s[66:67], 59, v0
	v_cndmask_b32_e64 v142, v142, v1, s[60:61]
	s_nop 1
	v_cndmask_b32_e64 v158, v158, v1, s[62:63]
	v_cndmask_b32_e64 v143, v143, v1, s[64:65]
	v_cndmask_b32_e64 v159, v159, v1, s[66:67]
.Lat_nomask_534:
	ds_read_b64_tr_b16 v[204:205], v250 offset:12288
	ds_read_b64_tr_b16 v[206:207], v250 offset:12800
	s_waitcnt lgkmcnt(6)
	v_mfma_f32_32x32x16_bf16 v[32:47], v[176:179], v[192:195], v[32:47]
	v_max3_f32 v2, v128, v129, v144
	v_max3_f32 v4, v130, v131, v145
	v_max3_f32 v2, v2, v146, v147
	ds_read_b64_tr_b16 v[192:193], v250 offset:1024
	ds_read_b64_tr_b16 v[194:195], v250 offset:1536
	s_waitcnt lgkmcnt(6)
	v_mfma_f32_32x32x16_bf16 v[48:63], v[176:179], v[196:199], v[48:63]
	v_max3_f32 v2, v2, v132, v133
	v_max3_f32 v4, v4, v134, v135
	v_max3_f32 v2, v2, v148, v149
	ds_read_b64_tr_b16 v[196:197], v250 offset:5120
	ds_read_b64_tr_b16 v[198:199], v250 offset:5632
	s_waitcnt lgkmcnt(6)
	v_mfma_f32_32x32x16_bf16 v[64:79], v[176:179], v[200:203], v[64:79]
	v_max3_f32 v4, v4, v150, v151
	v_max3_f32 v2, v2, v136, v137
	v_max3_f32 v4, v4, v138, v139
	ds_read_b64_tr_b16 v[200:201], v250 offset:9216
	ds_read_b64_tr_b16 v[202:203], v250 offset:9728
	s_waitcnt lgkmcnt(6)
	v_mfma_f32_32x32x16_bf16 v[80:95], v[176:179], v[204:207], v[80:95]
	v_max3_f32 v2, v2, v152, v153
	v_max3_f32 v4, v4, v154, v155
	v_max3_f32 v2, v2, v140, v141
	ds_read_b64_tr_b16 v[204:205], v250 offset:13312
	ds_read_b64_tr_b16 v[206:207], v250 offset:13824
	s_waitcnt lgkmcnt(6)
	v_mfma_f32_32x32x16_bf16 v[32:47], v[180:183], v[192:195], v[32:47]
	v_max3_f32 v4, v4, v142, v143
	v_max3_f32 v2, v2, v156, v157
	v_max3_f32 v4, v4, v158, v159
	ds_read_b64_tr_b16 v[192:193], v250 offset:2048
	ds_read_b64_tr_b16 v[194:195], v250 offset:2560
	s_waitcnt lgkmcnt(6)
	v_mfma_f32_32x32x16_bf16 v[48:63], v[180:183], v[196:199], v[48:63]
	v_max_f32_e32 v2, v2, v4
	v_mov_b32_e32 v4, v2
	s_nop 1
	v_permlane32_swap_b32_e32 v2, v4
	v_max_f32_e32 v2, v2, v4
	v_mov_b32_e32 v5, 0x41400000
	v_cmp_gt_f32_e32 vcc, v2, v5
	s_mov_b64 s[68:69], vcc
	s_cmp_lg_u64 vcc, 0
	s_cbranch_scc0 .Lat_noresc_443
	v_max_f32_e32 v4, 0, v2
	v_add_f32_e32 v248, v248, v4
	v_sub_f32_e32 v128, v128, v4
	v_sub_f32_e32 v129, v129, v4
	v_sub_f32_e32 v130, v130, v4
	v_sub_f32_e32 v131, v131, v4
	v_sub_f32_e32 v132, v132, v4
	v_sub_f32_e32 v133, v133, v4
	v_sub_f32_e32 v134, v134, v4
	v_sub_f32_e32 v135, v135, v4
	v_sub_f32_e32 v136, v136, v4
	v_sub_f32_e32 v137, v137, v4
	v_sub_f32_e32 v138, v138, v4
	v_sub_f32_e32 v139, v139, v4
	v_sub_f32_e32 v140, v140, v4
	v_sub_f32_e32 v141, v141, v4
	v_sub_f32_e32 v142, v142, v4
	v_sub_f32_e32 v143, v143, v4
	v_sub_f32_e32 v144, v144, v4
	v_sub_f32_e32 v145, v145, v4
	v_sub_f32_e32 v146, v146, v4
	v_sub_f32_e32 v147, v147, v4
	v_sub_f32_e32 v148, v148, v4
	v_sub_f32_e32 v149, v149, v4
	v_sub_f32_e32 v150, v150, v4
	v_sub_f32_e32 v151, v151, v4
	v_sub_f32_e32 v152, v152, v4
	v_sub_f32_e32 v153, v153, v4
	v_sub_f32_e32 v154, v154, v4
	v_sub_f32_e32 v155, v155, v4
	v_sub_f32_e32 v156, v156, v4
	v_sub_f32_e32 v157, v157, v4
	v_sub_f32_e32 v158, v158, v4
	v_sub_f32_e32 v159, v159, v4
	v_xor_b32_e32 v5, 0x80000000, v248
	v_mov_b32_e32 v160, v5
	v_mov_b32_e32 v161, v5
	v_mov_b32_e32 v162, v5
	v_mov_b32_e32 v163, v5
	v_mov_b32_e32 v164, v5
	v_mov_b32_e32 v165, v5
	v_mov_b32_e32 v166, v5
	v_mov_b32_e32 v167, v5
	v_mov_b32_e32 v168, v5
	v_mov_b32_e32 v169, v5
	v_mov_b32_e32 v170, v5
	v_mov_b32_e32 v171, v5
	v_mov_b32_e32 v172, v5
	v_mov_b32_e32 v173, v5
	v_mov_b32_e32 v174, v5
	v_mov_b32_e32 v175, v5
	v_xor_b32_e32 v6, 0x80000000, v4
	v_exp_f32_e32 v6, v6
	s_nop 0
	v_mul_f32_e32 v247, v247, v6
	v_and_b32_e32 v7, 31, v237
	v_lshl_add_u32 v7, v7, 2, v249
	v_cmp_eq_u32_e32 vcc, 0, v252
	s_and_saveexec_b64 s[60:61], vcc
	ds_write_b32 v7, v6
	s_or_b64 exec, exec, s[60:61]
.Lat_noresc_443:
	v_add_u32_e32 v3, s58, v244
	ds_read_b64_tr_b16 v[196:197], v250 offset:6144
	ds_read_b64_tr_b16 v[198:199], v250 offset:6656
	s_waitcnt lgkmcnt(6)
	v_mfma_f32_32x32x16_bf16 v[64:79], v[180:183], v[200:203], v[64:79]
	v_exp_f32_e32 v128, v128
	v_exp_f32_e32 v129, v129
	v_exp_f32_e32 v130, v130
	ds_read_b128 v[208:211], v3
	ds_read_b64_tr_b16 v[200:201], v250 offset:10240
	ds_read_b64_tr_b16 v[202:203], v250 offset:10752
	s_waitcnt lgkmcnt(7)
	v_mfma_f32_32x32x16_bf16 v[80:95], v[180:183], v[204:207], v[80:95]
	v_exp_f32_e32 v131, v131
	v_exp_f32_e32 v132, v132
	v_exp_f32_e32 v133, v133
	ds_read_b128 v[212:215], v3 offset:512
	ds_read_b64_tr_b16 v[204:205], v250 offset:14336
	ds_read_b64_tr_b16 v[206:207], v250 offset:14848
	s_waitcnt lgkmcnt(8)
	v_mfma_f32_32x32x16_bf16 v[32:47], v[184:187], v[192:195], v[32:47]
	v_exp_f32_e32 v134, v134
	v_exp_f32_e32 v135, v135
	v_exp_f32_e32 v136, v136
	ds_read_b128 v[216:219], v3 offset:2048
	ds_read_b64_tr_b16 v[192:193], v250 offset:3072
	ds_read_b64_tr_b16 v[194:195], v250 offset:3584
	s_waitcnt lgkmcnt(9)
	v_mfma_f32_32x32x16_bf16 v[48:63], v[184:187], v[196:199], v[48:63]
	v_exp_f32_e32 v137, v137
	v_exp_f32_e32 v138, v138
	v_exp_f32_e32 v139, v139
	ds_read_b128 v[220:223], v3 offset:2560
	ds_read_b64_tr_b16 v[196:197], v250 offset:7168
	ds_read_b64_tr_b16 v[198:199], v250 offset:7680
	s_waitcnt lgkmcnt(9)
	v_mfma_f32_32x32x16_bf16 v[64:79], v[184:187], v[200:203], v[64:79]
	v_exp_f32_e32 v140, v140
	v_exp_f32_e32 v141, v141
	v_exp_f32_e32 v142, v142
	ds_read_b128 v[224:227], v3 offset:4096
	ds_read_b64_tr_b16 v[200:201], v250 offset:11264
	ds_read_b64_tr_b16 v[202:203], v250 offset:11776
	s_waitcnt lgkmcnt(9)
	v_mfma_f32_32x32x16_bf16 v[80:95], v[184:187], v[204:207], v[80:95]
	v_exp_f32_e32 v143, v143
	v_exp_f32_e32 v144, v144
	v_exp_f32_e32 v145, v145
	ds_read_b128 v[228:231], v3 offset:4608
	ds_read_b64_tr_b16 v[204:205], v250 offset:15360
	ds_read_b64_tr_b16 v[206:207], v250 offset:15872
	s_waitcnt lgkmcnt(9)
	v_mfma_f32_32x32x16_bf16 v[32:47], v[188:191], v[192:195], v[32:47]
	v_exp_f32_e32 v146, v146
	v_exp_f32_e32 v147, v147
	v_exp_f32_e32 v148, v148
	ds_read_b128 v[232:235], v3 offset:6144
	s_waitcnt lgkmcnt(7)
	v_mfma_f32_32x32x16_bf16 v[48:63], v[188:191], v[196:199], v[48:63]
	v_exp_f32_e32 v149, v149
	v_exp_f32_e32 v150, v150
	v_exp_f32_e32 v151, v151
	ds_read_b128 v[240:243], v3 offset:6656
	s_waitcnt lgkmcnt(5)
	v_mfma_f32_32x32x16_bf16 v[64:79], v[188:191], v[200:203], v[64:79]
	v_exp_f32_e32 v152, v152
	v_exp_f32_e32 v153, v153
	v_exp_f32_e32 v154, v154
	v_exp_f32_e32 v155, v155
	s_waitcnt lgkmcnt(2)
	v_mfma_f32_32x32x16_bf16 v[80:95], v[188:191], v[204:207], v[80:95]
	v_exp_f32_e32 v156, v156
	v_exp_f32_e32 v157, v157
	v_exp_f32_e32 v158, v158
	v_exp_f32_e32 v159, v159
	s_waitcnt vmcnt(3) lgkmcnt(0)
	s_barrier
	s_cmp_lg_u64 s[68:69], 0
	s_cbranch_scc0 .Lat_norescO_443
	v_lshl_add_u32 v250, v252, 4, v249
	ds_read_b128 v[0:3], v250 offset:0
	ds_read_b128 v[4:7], v250 offset:32
	ds_read_b128 v[8:11], v250 offset:64
	ds_read_b128 v[12:15], v250 offset:96
	s_nop 7
	s_nop 7
	s_waitcnt lgkmcnt(0)
	v_mul_f32_e32 v32, v32, v0
	v_mul_f32_e32 v33, v33, v1
	v_mul_f32_e32 v34, v34, v2
	v_mul_f32_e32 v35, v35, v3
	v_mul_f32_e32 v36, v36, v4
	v_mul_f32_e32 v37, v37, v5
	v_mul_f32_e32 v38, v38, v6
	v_mul_f32_e32 v39, v39, v7
	v_mul_f32_e32 v40, v40, v8
	v_mul_f32_e32 v41, v41, v9
	v_mul_f32_e32 v42, v42, v10
	v_mul_f32_e32 v43, v43, v11
	v_mul_f32_e32 v44, v44, v12
	v_mul_f32_e32 v45, v45, v13
	v_mul_f32_e32 v46, v46, v14
	v_mul_f32_e32 v47, v47, v15
	v_mul_f32_e32 v48, v48, v0
	v_mul_f32_e32 v49, v49, v1
	v_mul_f32_e32 v50, v50, v2
	v_mul_f32_e32 v51, v51, v3
	v_mul_f32_e32 v52, v52, v4
	v_mul_f32_e32 v53, v53, v5
	v_mul_f32_e32 v54, v54, v6
	v_mul_f32_e32 v55, v55, v7
	v_mul_f32_e32 v56, v56, v8
	v_mul_f32_e32 v57, v57, v9
	v_mul_f32_e32 v58, v58, v10
	v_mul_f32_e32 v59, v59, v11
	v_mul_f32_e32 v60, v60, v12
	v_mul_f32_e32 v61, v61, v13
	v_mul_f32_e32 v62, v62, v14
	v_mul_f32_e32 v63, v63, v15
	v_mul_f32_e32 v64, v64, v0
	v_mul_f32_e32 v65, v65, v1
	v_mul_f32_e32 v66, v66, v2
	v_mul_f32_e32 v67, v67, v3
	v_mul_f32_e32 v68, v68, v4
	v_mul_f32_e32 v69, v69, v5
	v_mul_f32_e32 v70, v70, v6
	v_mul_f32_e32 v71, v71, v7
	v_mul_f32_e32 v72, v72, v8
	v_mul_f32_e32 v73, v73, v9
	v_mul_f32_e32 v74, v74, v10
	v_mul_f32_e32 v75, v75, v11
	v_mul_f32_e32 v76, v76, v12
	v_mul_f32_e32 v77, v77, v13
	v_mul_f32_e32 v78, v78, v14
	v_mul_f32_e32 v79, v79, v15
	v_mul_f32_e32 v80, v80, v0
	v_mul_f32_e32 v81, v81, v1
	v_mul_f32_e32 v82, v82, v2
	v_mul_f32_e32 v83, v83, v3
	v_mul_f32_e32 v84, v84, v4
	v_mul_f32_e32 v85, v85, v5
	v_mul_f32_e32 v86, v86, v6
	v_mul_f32_e32 v87, v87, v7
	v_mul_f32_e32 v88, v88, v8
	v_mul_f32_e32 v89, v89, v9
	v_mul_f32_e32 v90, v90, v10
	v_mul_f32_e32 v91, v91, v11
	v_mul_f32_e32 v92, v92, v12
	v_mul_f32_e32 v93, v93, v13
	v_mul_f32_e32 v94, v94, v14
	v_mul_f32_e32 v95, v95, v15
.Lat_norescO_443:
	s_mov_b32 s67, s56
	s_mov_b32 s56, s57
	s_mov_b32 s57, s58
	s_mov_b32 s58, s67
	s_add_u32 s46, s46, 1
	s_cmp_ge_u32 s46, s45
	s_cbranch_scc1 .Lat_drain
	s_lshl_b32 s60, s56, 1
	v_add_u32_e32 v250, s60, v245
	v_mov_b32_e32 v8, 0
	v_mov_b32_e32 v9, 0
	v_mov_b32_e32 v10, 0
	v_mov_b32_e32 v11, 0
	v_mfma_f32_32x32x16_bf16 v[96:111], v[208:211], v[16:19], v[160:175]
	v_add_f32_e32 v8, v8, v128
	v_add_f32_e32 v9, v9, v129
	v_add_f32_e32 v10, v10, v130
	v_add_f32_e32 v11, v11, v131
	v_cvt_pk_bf16_f32 v176, v128, v129
	v_cvt_pk_bf16_f32 v177, v130, v131
	v_mfma_f32_32x32x16_bf16 v[112:127], v[212:215], v[16:19], v[160:175]
	v_add_f32_e32 v8, v8, v132
	v_add_f32_e32 v9, v9, v133
	v_add_f32_e32 v10, v10, v134
	v_add_f32_e32 v11, v11, v135
	v_cvt_pk_bf16_f32 v178, v132, v133
	v_cvt_pk_bf16_f32 v179, v134, v135
	v_mfma_f32_32x32x16_bf16 v[96:111], v[216:219], v[20:23], v[96:111]
	v_add_f32_e32 v8, v8, v136
	v_add_f32_e32 v9, v9, v137
	v_add_f32_e32 v10, v10, v138
	v_add_f32_e32 v11, v11, v139
	v_cvt_pk_bf16_f32 v180, v136, v137
	v_cvt_pk_bf16_f32 v181, v138, v139
	v_mfma_f32_32x32x16_bf16 v[112:127], v[220:223], v[20:23], v[112:127]
	v_add_f32_e32 v8, v8, v140
	v_add_f32_e32 v9, v9, v141
	v_add_f32_e32 v10, v10, v142
	v_add_f32_e32 v11, v11, v143
	v_cvt_pk_bf16_f32 v182, v140, v141
	v_cvt_pk_bf16_f32 v183, v142, v143
	v_mfma_f32_32x32x16_bf16 v[96:111], v[224:227], v[24:27], v[96:111]
	v_add_f32_e32 v8, v8, v144
	v_add_f32_e32 v9, v9, v145
	v_add_f32_e32 v10, v10, v146
	v_add_f32_e32 v11, v11, v147
	v_cvt_pk_bf16_f32 v184, v144, v145
	v_cvt_pk_bf16_f32 v185, v146, v147
	v_mfma_f32_32x32x16_bf16 v[112:127], v[228:231], v[24:27], v[112:127]
	v_add_f32_e32 v8, v8, v148
	v_add_f32_e32 v9, v9, v149
	v_add_f32_e32 v10, v10, v150
	v_add_f32_e32 v11, v11, v151
	v_cvt_pk_bf16_f32 v186, v148, v149
	v_cvt_pk_bf16_f32 v187, v150, v151
	ds_read_b64_tr_b16 v[192:193], v250 offset:0
	ds_read_b64_tr_b16 v[194:195], v250 offset:512
	v_mfma_f32_32x32x16_bf16 v[96:111], v[232:235], v[28:31], v[96:111]
	v_add_f32_e32 v8, v8, v152
	v_add_f32_e32 v9, v9, v153
	v_add_f32_e32 v10, v10, v154
	v_add_f32_e32 v11, v11, v155
	v_cvt_pk_bf16_f32 v188, v152, v153
	v_cvt_pk_bf16_f32 v189, v154, v155
	ds_read_b64_tr_b16 v[196:197], v250 offset:4096
	ds_read_b64_tr_b16 v[198:199], v250 offset:4608
	v_mfma_f32_32x32x16_bf16 v[112:127], v[240:243], v[28:31], v[112:127]
	v_add_f32_e32 v8, v8, v156
	v_add_f32_e32 v9, v9, v157
	v_add_f32_e32 v10, v10, v158
	v_add_f32_e32 v11, v11, v159
	v_cvt_pk_bf16_f32 v190, v156, v157
	v_cvt_pk_bf16_f32 v191, v158, v159
	ds_read_b64_tr_b16 v[200:201], v250 offset:8192
	ds_read_b64_tr_b16 v[202:203], v250 offset:8704
	v_add_f32_e32 v8, v8, v9
	v_add_f32_e32 v10, v10, v11
	v_add_f32_e32 v8, v8, v10
	v_add_f32_e32 v247, v247, v8
	s_add_i32 m0, s57, s70
	s_nop 0
	global_load_lds_dwordx4 v238, s[74:75]
	s_add_u32 s74, s74, 0x10000
	s_addc_u32 s75, s75, 0
	s_lshl_b32 s60, s58, 1
	s_add_i32 s60, s60, s71
	s_mov_b32 m0, s60
	s_nop 0
	global_load_lds_dwordx4 v239, s[76:77]
	s_add_u32 s62, s76, 0x80
	s_addc_u32 s63, s77, 0
	s_add_i32 m0, s60, 0x2000
	s_nop 0
	global_load_lds_dwordx4 v239, s[62:63]
	s_add_u32 s76, s76, 0x10000
	s_addc_u32 s77, s77, 0
	s_cmp_lt_u32 s46, s72
	s_cbranch_scc1 .Lat_nomask_966
	s_sub_u32 s60, s46, s72
	s_lshl_b32 s60, s60, 6
	v_lshl_add_u32 v0, v252, 2, s60
	v_sub_u32_e32 v0, v246, v0
	v_mov_b32_e32 v1, 0xff800000
	v_cmp_gt_i32_e64 s[60:61], 0, v0
	v_cmp_gt_i32_e64 s[62:63], 32, v0
	v_cmp_gt_i32_e64 s[64:65], 1, v0
	v_cmp_gt_i32_e64 s[66:67], 33, v0
	v_cndmask_b32_e64 v96, v96, v1, s[60:61]
	v_cmp_gt_i32_e64 s[60:61], 2, v0
	v_cndmask_b32_e64 v112, v112, v1, s[62:63]
	v_cmp_gt_i32_e64 s[62:63], 34, v0
	v_cndmask_b32_e64 v97, v97, v1, s[64:65]
	v_cmp_gt_i32_e64 s[64:65], 3, v0
	v_cndmask_b32_e64 v113, v113, v1, s[66:67]
	v_cmp_gt_i32_e64 s[66:67], 35, v0
	v_cndmask_b32_e64 v98, v98, v1, s[60:61]
	v_cmp_gt_i32_e64 s[60:61], 8, v0
	v_cndmask_b32_e64 v114, v114, v1, s[62:63]
	v_cmp_gt_i32_e64 s[62:63], 40, v0
	v_cndmask_b32_e64 v99, v99, v1, s[64:65]
	v_cmp_gt_i32_e64 s[64:65], 9, v0
	v_cndmask_b32_e64 v115, v115, v1, s[66:67]
	v_cmp_gt_i32_e64 s[66:67], 41, v0
	v_cndmask_b32_e64 v100, v100, v1, s[60:61]
	v_cmp_gt_i32_e64 s[60:61], 10, v0
	v_cndmask_b32_e64 v116, v116, v1, s[62:63]
	v_cmp_gt_i32_e64 s[62:63], 42, v0
	v_cndmask_b32_e64 v101, v101, v1, s[64:65]
	v_cmp_gt_i32_e64 s[64:65], 11, v0
	v_cndmask_b32_e64 v117, v117, v1, s[66:67]
	v_cmp_gt_i32_e64 s[66:67], 43, v0
	v_cndmask_b32_e64 v102, v102, v1, s[60:61]
	v_cmp_gt_i32_e64 s[60:61], 16, v0
	v_cndmask_b32_e64 v118, v118, v1, s[62:63]
	v_cmp_gt_i32_e64 s[62:63], 48, v0
	v_cndmask_b32_e64 v103, v103, v1, s[64:65]
	v_cmp_gt_i32_e64 s[64:65], 17, v0
	v_cndmask_b32_e64 v119, v119, v1, s[66:67]
	v_cmp_gt_i32_e64 s[66:67], 49, v0
	v_cndmask_b32_e64 v104, v104, v1, s[60:61]
	v_cmp_gt_i32_e64 s[60:61], 18, v0
	v_cndmask_b32_e64 v120, v120, v1, s[62:63]
	v_cmp_gt_i32_e64 s[62:63], 50, v0
	v_cndmask_b32_e64 v105, v105, v1, s[64:65]
	v_cmp_gt_i32_e64 s[64:65], 19, v0
	v_cndmask_b32_e64 v121, v121, v1, s[66:67]
	v_cmp_gt_i32_e64 s[66:67], 51, v0
	v_cndmask_b32_e64 v106, v106, v1, s[60:61]
	v_cmp_gt_i32_e64 s[60:61], 24, v0
	v_cndmask_b32_e64 v122, v122, v1, s[62:63]
	v_cmp_gt_i32_e64 s[62:63], 56, v0
	v_cndmask_b32_e64 v107, v107, v1, s[64:65]
	v_cmp_gt_i32_e64 s[64:65], 25, v0
	v_cndmask_b32_e64 v123, v123, v1, s[66:67]
	v_cmp_gt_i32_e64 s[66:67], 57, v0
	v_cndmask_b32_e64 v108, v108, v1, s[60:61]
	v_cmp_gt_i32_e64 s[60:61], 26, v0
	v_cndmask_b32_e64 v124, v124, v1, s[62:63]
	v_cmp_gt_i32_e64 s[62:63], 58, v0
	v_cndmask_b32_e64 v109, v109, v1, s[64:65]
	v_cmp_gt_i32_e64 s[64:65], 27, v0
	v_cndmask_b32_e64 v125, v125, v1, s[66:67]
	v_cmp_gt_i32_e64 s[66:67], 59, v0
	v_cndmask_b32_e64 v110, v110, v1, s[60:61]
	s_nop 1
	v_cndmask_b32_e64 v126, v126, v1, s[62:63]
	v_cndmask_b32_e64 v111, v111, v1, s[64:65]
	v_cndmask_b32_e64 v127, v127, v1, s[66:67]
.Lat_nomask_966:
	ds_read_b64_tr_b16 v[204:205], v250 offset:12288
	ds_read_b64_tr_b16 v[206:207], v250 offset:12800
	s_waitcnt lgkmcnt(6)
	v_mfma_f32_32x32x16_bf16 v[32:47], v[176:179], v[192:195], v[32:47]
	v_max3_f32 v2, v96, v97, v112
	v_max3_f32 v4, v98, v99, v113
	v_max3_f32 v2, v2, v114, v115
	ds_read_b64_tr_b16 v[192:193], v250 offset:1024
	ds_read_b64_tr_b16 v[194:195], v250 offset:1536
	s_waitcnt lgkmcnt(6)
	v_mfma_f32_32x32x16_bf16 v[48:63], v[176:179], v[196:199], v[48:63]
	v_max3_f32 v2, v2, v100, v101
	v_max3_f32 v4, v4, v102, v103
	v_max3_f32 v2, v2, v116, v117
	ds_read_b64_tr_b16 v[196:197], v250 offset:5120
	ds_read_b64_tr_b16 v[198:199], v250 offset:5632
	s_waitcnt lgkmcnt(6)
	v_mfma_f32_32x32x16_bf16 v[64:79], v[176:179], v[200:203], v[64:79]
	v_max3_f32 v4, v4, v118, v119
	v_max3_f32 v2, v2, v104, v105
	v_max3_f32 v4, v4, v106, v107
	ds_read_b64_tr_b16 v[200:201], v250 offset:9216
	ds_read_b64_tr_b16 v[202:203], v250 offset:9728
	s_waitcnt lgkmcnt(6)
	v_mfma_f32_32x32x16_bf16 v[80:95], v[176:179], v[204:207], v[80:95]
	v_max3_f32 v2, v2, v120, v121
	v_max3_f32 v4, v4, v122, v123
	v_max3_f32 v2, v2, v108, v109
	ds_read_b64_tr_b16 v[204:205], v250 offset:13312
	ds_read_b64_tr_b16 v[206:207], v250 offset:13824
	s_waitcnt lgkmcnt(6)
	v_mfma_f32_32x32x16_bf16 v[32:47], v[180:183], v[192:195], v[32:47]
	v_max3_f32 v4, v4, v110, v111
	v_max3_f32 v2, v2, v124, v125
	v_max3_f32 v4, v4, v126, v127
	ds_read_b64_tr_b16 v[192:193], v250 offset:2048
	ds_read_b64_tr_b16 v[194:195], v250 offset:2560
	s_waitcnt lgkmcnt(6)
	v_mfma_f32_32x32x16_bf16 v[48:63], v[180:183], v[196:199], v[48:63]
	v_max_f32_e32 v2, v2, v4
	v_mov_b32_e32 v4, v2
	s_nop 1
	v_permlane32_swap_b32_e32 v2, v4
	v_max_f32_e32 v2, v2, v4
	v_mov_b32_e32 v5, 0x41400000
	v_cmp_gt_f32_e32 vcc, v2, v5
	s_mov_b64 s[68:69], vcc
	s_cmp_lg_u64 vcc, 0
	s_cbranch_scc0 .Lat_noresc_875
	v_max_f32_e32 v4, 0, v2
	v_add_f32_e32 v248, v248, v4
	v_sub_f32_e32 v96, v96, v4
	v_sub_f32_e32 v97, v97, v4
	v_sub_f32_e32 v98, v98, v4
	v_sub_f32_e32 v99, v99, v4
	v_sub_f32_e32 v100, v100, v4
	v_sub_f32_e32 v101, v101, v4
	v_sub_f32_e32 v102, v102, v4
	v_sub_f32_e32 v103, v103, v4
	v_sub_f32_e32 v104, v104, v4
	v_sub_f32_e32 v105, v105, v4
	v_sub_f32_e32 v106, v106, v4
	v_sub_f32_e32 v107, v107, v4
	v_sub_f32_e32 v108, v108, v4
	v_sub_f32_e32 v109, v109, v4
	v_sub_f32_e32 v110, v110, v4
	v_sub_f32_e32 v111, v111, v4
	v_sub_f32_e32 v112, v112, v4
	v_sub_f32_e32 v113, v113, v4
	v_sub_f32_e32 v114, v114, v4
	v_sub_f32_e32 v115, v115, v4
	v_sub_f32_e32 v116, v116, v4
	v_sub_f32_e32 v117, v117, v4
	v_sub_f32_e32 v118, v118, v4
	v_sub_f32_e32 v119, v119, v4
	v_sub_f32_e32 v120, v120, v4
	v_sub_f32_e32 v121, v121, v4
	v_sub_f32_e32 v122, v122, v4
	v_sub_f32_e32 v123, v123, v4
	v_sub_f32_e32 v124, v124, v4
	v_sub_f32_e32 v125, v125, v4
	v_sub_f32_e32 v126, v126, v4
	v_sub_f32_e32 v127, v127, v4
	v_xor_b32_e32 v5, 0x80000000, v248
	v_mov_b32_e32 v160, v5
	v_mov_b32_e32 v161, v5
	v_mov_b32_e32 v162, v5
	v_mov_b32_e32 v163, v5
	v_mov_b32_e32 v164, v5
	v_mov_b32_e32 v165, v5
	v_mov_b32_e32 v166, v5
	v_mov_b32_e32 v167, v5
	v_mov_b32_e32 v168, v5
	v_mov_b32_e32 v169, v5
	v_mov_b32_e32 v170, v5
	v_mov_b32_e32 v171, v5
	v_mov_b32_e32 v172, v5
	v_mov_b32_e32 v173, v5
	v_mov_b32_e32 v174, v5
	v_mov_b32_e32 v175, v5
	v_xor_b32_e32 v6, 0x80000000, v4
	v_exp_f32_e32 v6, v6
	s_nop 0
	v_mul_f32_e32 v247, v247, v6
	v_and_b32_e32 v7, 31, v237
	v_lshl_add_u32 v7, v7, 2, v249
	v_cmp_eq_u32_e32 vcc, 0, v252
	s_and_saveexec_b64 s[60:61], vcc
	ds_write_b32 v7, v6
	s_or_b64 exec, exec, s[60:61]
.Lat_noresc_875:
	v_add_u32_e32 v3, s58, v244
	ds_read_b64_tr_b16 v[196:197], v250 offset:6144
	ds_read_b64_tr_b16 v[198:199], v250 offset:6656
	s_waitcnt lgkmcnt(6)
	v_mfma_f32_32x32x16_bf16 v[64:79], v[180:183], v[200:203], v[64:79]
	v_exp_f32_e32 v96, v96
	v_exp_f32_e32 v97, v97
	v_exp_f32_e32 v98, v98
	ds_read_b128 v[208:211], v3
	ds_read_b64_tr_b16 v[200:201], v250 offset:10240
	ds_read_b64_tr_b16 v[202:203], v250 offset:10752
	s_waitcnt lgkmcnt(7)
	v_mfma_f32_32x32x16_bf16 v[80:95], v[180:183], v[204:207], v[80:95]
	v_exp_f32_e32 v99, v99
	v_exp_f32_e32 v100, v100
	v_exp_f32_e32 v101, v101
	ds_read_b128 v[212:215], v3 offset:512
	ds_read_b64_tr_b16 v[204:205], v250 offset:14336
	ds_read_b64_tr_b16 v[206:207], v250 offset:14848
	s_waitcnt lgkmcnt(8)
	v_mfma_f32_32x32x16_bf16 v[32:47], v[184:187], v[192:195], v[32:47]
	v_exp_f32_e32 v102, v102
	v_exp_f32_e32 v103, v103
	v_exp_f32_e32 v104, v104
	ds_read_b128 v[216:219], v3 offset:2048
	ds_read_b64_tr_b16 v[192:193], v250 offset:3072
	ds_read_b64_tr_b16 v[194:195], v250 offset:3584
	s_waitcnt lgkmcnt(9)
	v_mfma_f32_32x32x16_bf16 v[48:63], v[184:187], v[196:199], v[48:63]
	v_exp_f32_e32 v105, v105
	v_exp_f32_e32 v106, v106
	v_exp_f32_e32 v107, v107
	ds_read_b128 v[220:223], v3 offset:2560
	ds_read_b64_tr_b16 v[196:197], v250 offset:7168
	ds_read_b64_tr_b16 v[198:199], v250 offset:7680
	s_waitcnt lgkmcnt(9)
	v_mfma_f32_32x32x16_bf16 v[64:79], v[184:187], v[200:203], v[64:79]
	v_exp_f32_e32 v108, v108
	v_exp_f32_e32 v109, v109
	v_exp_f32_e32 v110, v110
	ds_read_b128 v[224:227], v3 offset:4096
	ds_read_b64_tr_b16 v[200:201], v250 offset:11264
	ds_read_b64_tr_b16 v[202:203], v250 offset:11776
	s_waitcnt lgkmcnt(9)
	v_mfma_f32_32x32x16_bf16 v[80:95], v[184:187], v[204:207], v[80:95]
	v_exp_f32_e32 v111, v111
	v_exp_f32_e32 v112, v112
	v_exp_f32_e32 v113, v113
	ds_read_b128 v[228:231], v3 offset:4608
	ds_read_b64_tr_b16 v[204:205], v250 offset:15360
	ds_read_b64_tr_b16 v[206:207], v250 offset:15872
	s_waitcnt lgkmcnt(9)
	v_mfma_f32_32x32x16_bf16 v[32:47], v[188:191], v[192:195], v[32:47]
	v_exp_f32_e32 v114, v114
	v_exp_f32_e32 v115, v115
	v_exp_f32_e32 v116, v116
	ds_read_b128 v[232:235], v3 offset:6144
	s_waitcnt lgkmcnt(7)
	v_mfma_f32_32x32x16_bf16 v[48:63], v[188:191], v[196:199], v[48:63]
	v_exp_f32_e32 v117, v117
	v_exp_f32_e32 v118, v118
	v_exp_f32_e32 v119, v119
	ds_read_b128 v[240:243], v3 offset:6656
	s_waitcnt lgkmcnt(5)
	v_mfma_f32_32x32x16_bf16 v[64:79], v[188:191], v[200:203], v[64:79]
	v_exp_f32_e32 v120, v120
	v_exp_f32_e32 v121, v121
	v_exp_f32_e32 v122, v122
	v_exp_f32_e32 v123, v123
	s_waitcnt lgkmcnt(2)
	v_mfma_f32_32x32x16_bf16 v[80:95], v[188:191], v[204:207], v[80:95]
	v_exp_f32_e32 v124, v124
	v_exp_f32_e32 v125, v125
	v_exp_f32_e32 v126, v126
	v_exp_f32_e32 v127, v127
	s_waitcnt vmcnt(3) lgkmcnt(0)
	s_barrier
	s_cmp_lg_u64 s[68:69], 0
	s_cbranch_scc0 .Lat_norescO_875
	v_lshl_add_u32 v250, v252, 4, v249
	ds_read_b128 v[0:3], v250 offset:0
	ds_read_b128 v[4:7], v250 offset:32
	ds_read_b128 v[8:11], v250 offset:64
	ds_read_b128 v[12:15], v250 offset:96
	s_nop 7
	s_nop 7
	s_waitcnt lgkmcnt(0)
	v_mul_f32_e32 v32, v32, v0
	v_mul_f32_e32 v33, v33, v1
	v_mul_f32_e32 v34, v34, v2
	v_mul_f32_e32 v35, v35, v3
	v_mul_f32_e32 v36, v36, v4
	v_mul_f32_e32 v37, v37, v5
	v_mul_f32_e32 v38, v38, v6
	v_mul_f32_e32 v39, v39, v7
	v_mul_f32_e32 v40, v40, v8
	v_mul_f32_e32 v41, v41, v9
	v_mul_f32_e32 v42, v42, v10
	v_mul_f32_e32 v43, v43, v11
	v_mul_f32_e32 v44, v44, v12
	v_mul_f32_e32 v45, v45, v13
	v_mul_f32_e32 v46, v46, v14
	v_mul_f32_e32 v47, v47, v15
	v_mul_f32_e32 v48, v48, v0
	v_mul_f32_e32 v49, v49, v1
	v_mul_f32_e32 v50, v50, v2
	v_mul_f32_e32 v51, v51, v3
	v_mul_f32_e32 v52, v52, v4
	v_mul_f32_e32 v53, v53, v5
	v_mul_f32_e32 v54, v54, v6
	v_mul_f32_e32 v55, v55, v7
	v_mul_f32_e32 v56, v56, v8
	v_mul_f32_e32 v57, v57, v9
	v_mul_f32_e32 v58, v58, v10
	v_mul_f32_e32 v59, v59, v11
	v_mul_f32_e32 v60, v60, v12
	v_mul_f32_e32 v61, v61, v13
	v_mul_f32_e32 v62, v62, v14
	v_mul_f32_e32 v63, v63, v15
	v_mul_f32_e32 v64, v64, v0
	v_mul_f32_e32 v65, v65, v1
	v_mul_f32_e32 v66, v66, v2
	v_mul_f32_e32 v67, v67, v3
	v_mul_f32_e32 v68, v68, v4
	v_mul_f32_e32 v69, v69, v5
	v_mul_f32_e32 v70, v70, v6
	v_mul_f32_e32 v71, v71, v7
	v_mul_f32_e32 v72, v72, v8
	v_mul_f32_e32 v73, v73, v9
	v_mul_f32_e32 v74, v74, v10
	v_mul_f32_e32 v75, v75, v11
	v_mul_f32_e32 v76, v76, v12
	v_mul_f32_e32 v77, v77, v13
	v_mul_f32_e32 v78, v78, v14
	v_mul_f32_e32 v79, v79, v15
	v_mul_f32_e32 v80, v80, v0
	v_mul_f32_e32 v81, v81, v1
	v_mul_f32_e32 v82, v82, v2
	v_mul_f32_e32 v83, v83, v3
	v_mul_f32_e32 v84, v84, v4
	v_mul_f32_e32 v85, v85, v5
	v_mul_f32_e32 v86, v86, v6
	v_mul_f32_e32 v87, v87, v7
	v_mul_f32_e32 v88, v88, v8
	v_mul_f32_e32 v89, v89, v9
	v_mul_f32_e32 v90, v90, v10
	v_mul_f32_e32 v91, v91, v11
	v_mul_f32_e32 v92, v92, v12
	v_mul_f32_e32 v93, v93, v13
	v_mul_f32_e32 v94, v94, v14
	v_mul_f32_e32 v95, v95, v15

.Lat_drain:
	v_mov_b32_e32 v8, 0
	v_mov_b32_e32 v9, 0
	v_mov_b32_e32 v10, 0
	v_mov_b32_e32 v11, 0
	v_add_f32_e32 v8, v8, v128
	v_add_f32_e32 v9, v9, v129
	v_add_f32_e32 v10, v10, v130
	v_add_f32_e32 v11, v11, v131
	v_cvt_pk_bf16_f32 v176, v128, v129
	v_cvt_pk_bf16_f32 v177, v130, v131
	v_add_f32_e32 v8, v8, v132
	v_add_f32_e32 v9, v9, v133
	v_add_f32_e32 v10, v10, v134
	v_add_f32_e32 v11, v11, v135
	v_cvt_pk_bf16_f32 v178, v132, v133
	v_cvt_pk_bf16_f32 v179, v134, v135
	v_add_f32_e32 v8, v8, v136
	v_add_f32_e32 v9, v9, v137
	v_add_f32_e32 v10, v10, v138
	v_add_f32_e32 v11, v11, v139
	v_cvt_pk_bf16_f32 v180, v136, v137
	v_cvt_pk_bf16_f32 v181, v138, v139
	v_add_f32_e32 v8, v8, v140
	v_add_f32_e32 v9, v9, v141
	v_add_f32_e32 v10, v10, v142
	v_add_f32_e32 v11, v11, v143
	v_cvt_pk_bf16_f32 v182, v140, v141
	v_cvt_pk_bf16_f32 v183, v142, v143
	v_add_f32_e32 v8, v8, v144
	v_add_f32_e32 v9, v9, v145
	v_add_f32_e32 v10, v10, v146
	v_add_f32_e32 v11, v11, v147
	v_cvt_pk_bf16_f32 v184, v144, v145
	v_cvt_pk_bf16_f32 v185, v146, v147
	v_add_f32_e32 v8, v8, v148
	v_add_f32_e32 v9, v9, v149
	v_add_f32_e32 v10, v10, v150
	v_add_f32_e32 v11, v11, v151
	v_cvt_pk_bf16_f32 v186, v148, v149
	v_cvt_pk_bf16_f32 v187, v150, v151
	v_add_f32_e32 v8, v8, v152
	v_add_f32_e32 v9, v9, v153
	v_add_f32_e32 v10, v10, v154
	v_add_f32_e32 v11, v11, v155
	v_cvt_pk_bf16_f32 v188, v152, v153
	v_cvt_pk_bf16_f32 v189, v154, v155
	v_add_f32_e32 v8, v8, v156
	v_add_f32_e32 v9, v9, v157
	v_add_f32_e32 v10, v10, v158
	v_add_f32_e32 v11, v11, v159
	v_cvt_pk_bf16_f32 v190, v156, v157
	v_cvt_pk_bf16_f32 v191, v158, v159
	v_add_f32_e32 v8, v8, v9
	v_add_f32_e32 v10, v10, v11
	v_add_f32_e32 v8, v8, v10
	v_add_f32_e32 v247, v247, v8
	s_lshl_b32 s60, s56, 1
	v_add_u32_e32 v250, s60, v245
	ds_read_b64_tr_b16 v[192:193], v250 offset:0
	ds_read_b64_tr_b16 v[194:195], v250 offset:512
	ds_read_b64_tr_b16 v[196:197], v250 offset:4096
	ds_read_b64_tr_b16 v[198:199], v250 offset:4608
	ds_read_b64_tr_b16 v[200:201], v250 offset:8192
	ds_read_b64_tr_b16 v[202:203], v250 offset:8704
	ds_read_b64_tr_b16 v[204:205], v250 offset:12288
	ds_read_b64_tr_b16 v[206:207], v250 offset:12800
	s_waitcnt lgkmcnt(6)
	v_mfma_f32_32x32x16_bf16 v[32:47], v[176:179], v[192:195], v[32:47]
	ds_read_b64_tr_b16 v[192:193], v250 offset:1024
	ds_read_b64_tr_b16 v[194:195], v250 offset:1536
	s_waitcnt lgkmcnt(6)
	v_mfma_f32_32x32x16_bf16 v[48:63], v[176:179], v[196:199], v[48:63]
	ds_read_b64_tr_b16 v[196:197], v250 offset:5120
	ds_read_b64_tr_b16 v[198:199], v250 offset:5632
	s_waitcnt lgkmcnt(6)
	v_mfma_f32_32x32x16_bf16 v[64:79], v[176:179], v[200:203], v[64:79]
	ds_read_b64_tr_b16 v[200:201], v250 offset:9216
	ds_read_b64_tr_b16 v[202:203], v250 offset:9728
	s_waitcnt lgkmcnt(6)
	v_mfma_f32_32x32x16_bf16 v[80:95], v[176:179], v[204:207], v[80:95]
	ds_read_b64_tr_b16 v[204:205], v250 offset:13312
	ds_read_b64_tr_b16 v[206:207], v250 offset:13824
	s_waitcnt lgkmcnt(6)
	v_mfma_f32_32x32x16_bf16 v[32:47], v[180:183], v[192:195], v[32:47]
	ds_read_b64_tr_b16 v[192:193], v250 offset:2048
	ds_read_b64_tr_b16 v[194:195], v250 offset:2560
	s_waitcnt lgkmcnt(6)
	v_mfma_f32_32x32x16_bf16 v[48:63], v[180:183], v[196:199], v[48:63]
	ds_read_b64_tr_b16 v[196:197], v250 offset:6144
	ds_read_b64_tr_b16 v[198:199], v250 offset:6656
	s_waitcnt lgkmcnt(6)
	v_mfma_f32_32x32x16_bf16 v[64:79], v[180:183], v[200:203], v[64:79]
	ds_read_b64_tr_b16 v[200:201], v250 offset:10240
	ds_read_b64_tr_b16 v[202:203], v250 offset:10752
	s_waitcnt lgkmcnt(6)
	v_mfma_f32_32x32x16_bf16 v[80:95], v[180:183], v[204:207], v[80:95]
	ds_read_b64_tr_b16 v[204:205], v250 offset:14336
	ds_read_b64_tr_b16 v[206:207], v250 offset:14848
	s_waitcnt lgkmcnt(6)
	v_mfma_f32_32x32x16_bf16 v[32:47], v[184:187], v[192:195], v[32:47]
	ds_read_b64_tr_b16 v[192:193], v250 offset:3072
	ds_read_b64_tr_b16 v[194:195], v250 offset:3584
	s_waitcnt lgkmcnt(6)
	v_mfma_f32_32x32x16_bf16 v[48:63], v[184:187], v[196:199], v[48:63]
	ds_read_b64_tr_b16 v[196:197], v250 offset:7168
	ds_read_b64_tr_b16 v[198:199], v250 offset:7680
	s_waitcnt lgkmcnt(6)
	v_mfma_f32_32x32x16_bf16 v[64:79], v[184:187], v[200:203], v[64:79]
	ds_read_b64_tr_b16 v[200:201], v250 offset:11264
	ds_read_b64_tr_b16 v[202:203], v250 offset:11776
	s_waitcnt lgkmcnt(6)
	v_mfma_f32_32x32x16_bf16 v[80:95], v[184:187], v[204:207], v[80:95]
	ds_read_b64_tr_b16 v[204:205], v250 offset:15360
	ds_read_b64_tr_b16 v[206:207], v250 offset:15872
	s_waitcnt lgkmcnt(6)
	v_mfma_f32_32x32x16_bf16 v[32:47], v[188:191], v[192:195], v[32:47]
	s_waitcnt lgkmcnt(4)
	v_mfma_f32_32x32x16_bf16 v[48:63], v[188:191], v[196:199], v[48:63]
	s_waitcnt lgkmcnt(2)
	v_mfma_f32_32x32x16_bf16 v[64:79], v[188:191], v[200:203], v[64:79]
	s_waitcnt lgkmcnt(0)
	v_mfma_f32_32x32x16_bf16 v[80:95], v[188:191], v[204:207], v[80:95]
	v_mov_b32_e32 v250, v247
	v_mov_b32_e32 v251, v247
	s_nop 1
	v_permlane32_swap_b32_e32 v250, v251
	v_add_f32_e32 v250, v250, v251
	s_waitcnt vmcnt(0) lgkmcnt(0)
	s_barrier
	v_and_b32_e32 v244, 31, v237
	v_lshl_add_u32 v244, v244, 2, v249
	v_cmp_eq_u32_e32 vcc, 0, v252
	s_and_saveexec_b64 s[60:61], vcc
	ds_write_b32 v244, v250 offset:128
	s_or_b64 exec, exec, s[60:61]
	s_waitcnt lgkmcnt(0)
	v_lshl_add_u32 v250, v252, 4, v249
	ds_read_b128 v[0:3], v250 offset:128
	ds_read_b128 v[4:7], v250 offset:160
	ds_read_b128 v[8:11], v250 offset:192
	ds_read_b128 v[12:15], v250 offset:224
	s_waitcnt lgkmcnt(0)
	v_rcp_f32_e32 v0, v0
	v_rcp_f32_e32 v1, v1
	v_rcp_f32_e32 v2, v2
	v_rcp_f32_e32 v3, v3
	v_rcp_f32_e32 v4, v4
	v_rcp_f32_e32 v5, v5
	v_rcp_f32_e32 v6, v6
	v_rcp_f32_e32 v7, v7
	v_rcp_f32_e32 v8, v8
	v_rcp_f32_e32 v9, v9
	v_rcp_f32_e32 v10, v10
	v_rcp_f32_e32 v11, v11
	v_rcp_f32_e32 v12, v12
	v_rcp_f32_e32 v13, v13
	v_rcp_f32_e32 v14, v14
	v_rcp_f32_e32 v15, v15
	s_nop 7
	s_nop 7
	s_lshl_b32 s60, s47, 13
	v_and_b32_e32 v250, 31, v237
	v_lshlrev_b32_e32 v250, 1, v250
	v_add_u32_e32 v250, s60, v250
	v_lshlrev_b32_e32 v251, 10, v252
	v_add_u32_e32 v250, v250, v251
	v_mul_f32_e32 v251, v32, v0
	v_cvt_pk_bf16_f32 v251, v251, v251
	ds_write_b16 v250, v251 offset:0
	v_mul_f32_e32 v251, v48, v0
	v_cvt_pk_bf16_f32 v251, v251, v251
	ds_write_b16 v250, v251 offset:64
	v_mul_f32_e32 v251, v64, v0
	v_cvt_pk_bf16_f32 v251, v251, v251
	ds_write_b16 v250, v251 offset:128
	v_mul_f32_e32 v251, v80, v0
	v_cvt_pk_bf16_f32 v251, v251, v251
	ds_write_b16 v250, v251 offset:192
	v_mul_f32_e32 v251, v33, v1
	v_cvt_pk_bf16_f32 v251, v251, v251
	ds_write_b16 v250, v251 offset:256
	v_mul_f32_e32 v251, v49, v1
	v_cvt_pk_bf16_f32 v251, v251, v251
	ds_write_b16 v250, v251 offset:320
	v_mul_f32_e32 v251, v65, v1
	v_cvt_pk_bf16_f32 v251, v251, v251
	ds_write_b16 v250, v251 offset:384
	v_mul_f32_e32 v251, v81, v1
	v_cvt_pk_bf16_f32 v251, v251, v251
	ds_write_b16 v250, v251 offset:448
	v_mul_f32_e32 v251, v34, v2
	v_cvt_pk_bf16_f32 v251, v251, v251
	ds_write_b16 v250, v251 offset:512
	v_mul_f32_e32 v251, v50, v2
	v_cvt_pk_bf16_f32 v251, v251, v251
	ds_write_b16 v250, v251 offset:576
	v_mul_f32_e32 v251, v66, v2
	v_cvt_pk_bf16_f32 v251, v251, v251
	ds_write_b16 v250, v251 offset:640
	v_mul_f32_e32 v251, v82, v2
	v_cvt_pk_bf16_f32 v251, v251, v251
	ds_write_b16 v250, v251 offset:704
	v_mul_f32_e32 v251, v35, v3
	v_cvt_pk_bf16_f32 v251, v251, v251
	ds_write_b16 v250, v251 offset:768
	v_mul_f32_e32 v251, v51, v3
	v_cvt_pk_bf16_f32 v251, v251, v251
	ds_write_b16 v250, v251 offset:832
	v_mul_f32_e32 v251, v67, v3
	v_cvt_pk_bf16_f32 v251, v251, v251
	ds_write_b16 v250, v251 offset:896
	v_mul_f32_e32 v251, v83, v3
	v_cvt_pk_bf16_f32 v251, v251, v251
	ds_write_b16 v250, v251 offset:960
	v_mul_f32_e32 v251, v36, v4
	v_cvt_pk_bf16_f32 v251, v251, v251
	ds_write_b16 v250, v251 offset:2048
	v_mul_f32_e32 v251, v52, v4
	v_cvt_pk_bf16_f32 v251, v251, v251
	ds_write_b16 v250, v251 offset:2112
	v_mul_f32_e32 v251, v68, v4
	v_cvt_pk_bf16_f32 v251, v251, v251
	ds_write_b16 v250, v251 offset:2176
	v_mul_f32_e32 v251, v84, v4
	v_cvt_pk_bf16_f32 v251, v251, v251
	ds_write_b16 v250, v251 offset:2240
	v_mul_f32_e32 v251, v37, v5
	v_cvt_pk_bf16_f32 v251, v251, v251
	ds_write_b16 v250, v251 offset:2304
	v_mul_f32_e32 v251, v53, v5
	v_cvt_pk_bf16_f32 v251, v251, v251
	ds_write_b16 v250, v251 offset:2368
	v_mul_f32_e32 v251, v69, v5
	v_cvt_pk_bf16_f32 v251, v251, v251
	ds_write_b16 v250, v251 offset:2432
	v_mul_f32_e32 v251, v85, v5
	v_cvt_pk_bf16_f32 v251, v251, v251
	ds_write_b16 v250, v251 offset:2496
	v_mul_f32_e32 v251, v38, v6
	v_cvt_pk_bf16_f32 v251, v251, v251
	ds_write_b16 v250, v251 offset:2560
	v_mul_f32_e32 v251, v54, v6
	v_cvt_pk_bf16_f32 v251, v251, v251
	ds_write_b16 v250, v251 offset:2624
	v_mul_f32_e32 v251, v70, v6
	v_cvt_pk_bf16_f32 v251, v251, v251
	ds_write_b16 v250, v251 offset:2688
	v_mul_f32_e32 v251, v86, v6
	v_cvt_pk_bf16_f32 v251, v251, v251
	ds_write_b16 v250, v251 offset:2752
	v_mul_f32_e32 v251, v39, v7
	v_cvt_pk_bf16_f32 v251, v251, v251
	ds_write_b16 v250, v251 offset:2816
	v_mul_f32_e32 v251, v55, v7
	v_cvt_pk_bf16_f32 v251, v251, v251
	ds_write_b16 v250, v251 offset:2880
	v_mul_f32_e32 v251, v71, v7
	v_cvt_pk_bf16_f32 v251, v251, v251
	ds_write_b16 v250, v251 offset:2944
	v_mul_f32_e32 v251, v87, v7
	v_cvt_pk_bf16_f32 v251, v251, v251
	ds_write_b16 v250, v251 offset:3008
	v_mul_f32_e32 v251, v40, v8
	v_cvt_pk_bf16_f32 v251, v251, v251
	ds_write_b16 v250, v251 offset:4096
	v_mul_f32_e32 v251, v56, v8
	v_cvt_pk_bf16_f32 v251, v251, v251
	ds_write_b16 v250, v251 offset:4160
	v_mul_f32_e32 v251, v72, v8
	v_cvt_pk_bf16_f32 v251, v251, v251
	ds_write_b16 v250, v251 offset:4224
	v_mul_f32_e32 v251, v88, v8
	v_cvt_pk_bf16_f32 v251, v251, v251
	ds_write_b16 v250, v251 offset:4288
	v_mul_f32_e32 v251, v41, v9
	v_cvt_pk_bf16_f32 v251, v251, v251
	ds_write_b16 v250, v251 offset:4352
	v_mul_f32_e32 v251, v57, v9
	v_cvt_pk_bf16_f32 v251, v251, v251
	ds_write_b16 v250, v251 offset:4416
	v_mul_f32_e32 v251, v73, v9
	v_cvt_pk_bf16_f32 v251, v251, v251
	ds_write_b16 v250, v251 offset:4480
	v_mul_f32_e32 v251, v89, v9
	v_cvt_pk_bf16_f32 v251, v251, v251
	ds_write_b16 v250, v251 offset:4544
	v_mul_f32_e32 v251, v42, v10
	v_cvt_pk_bf16_f32 v251, v251, v251
	ds_write_b16 v250, v251 offset:4608
	v_mul_f32_e32 v251, v58, v10
	v_cvt_pk_bf16_f32 v251, v251, v251
	ds_write_b16 v250, v251 offset:4672
	v_mul_f32_e32 v251, v74, v10
	v_cvt_pk_bf16_f32 v251, v251, v251
	ds_write_b16 v250, v251 offset:4736
	v_mul_f32_e32 v251, v90, v10
	v_cvt_pk_bf16_f32 v251, v251, v251
	ds_write_b16 v250, v251 offset:4800
	v_mul_f32_e32 v251, v43, v11
	v_cvt_pk_bf16_f32 v251, v251, v251
	ds_write_b16 v250, v251 offset:4864
	v_mul_f32_e32 v251, v59, v11
	v_cvt_pk_bf16_f32 v251, v251, v251
	ds_write_b16 v250, v251 offset:4928
	v_mul_f32_e32 v251, v75, v11
	v_cvt_pk_bf16_f32 v251, v251, v251
	ds_write_b16 v250, v251 offset:4992
	v_mul_f32_e32 v251, v91, v11
	v_cvt_pk_bf16_f32 v251, v251, v251
	ds_write_b16 v250, v251 offset:5056
	v_mul_f32_e32 v251, v44, v12
	v_cvt_pk_bf16_f32 v251, v251, v251
	ds_write_b16 v250, v251 offset:6144
	v_mul_f32_e32 v251, v60, v12
	v_cvt_pk_bf16_f32 v251, v251, v251
	ds_write_b16 v250, v251 offset:6208
	v_mul_f32_e32 v251, v76, v12
	v_cvt_pk_bf16_f32 v251, v251, v251
	ds_write_b16 v250, v251 offset:6272
	v_mul_f32_e32 v251, v92, v12
	v_cvt_pk_bf16_f32 v251, v251, v251
	ds_write_b16 v250, v251 offset:6336
	v_mul_f32_e32 v251, v45, v13
	v_cvt_pk_bf16_f32 v251, v251, v251
	ds_write_b16 v250, v251 offset:6400
	v_mul_f32_e32 v251, v61, v13
	v_cvt_pk_bf16_f32 v251, v251, v251
	ds_write_b16 v250, v251 offset:6464
	v_mul_f32_e32 v251, v77, v13
	v_cvt_pk_bf16_f32 v251, v251, v251
	ds_write_b16 v250, v251 offset:6528
	v_mul_f32_e32 v251, v93, v13
	v_cvt_pk_bf16_f32 v251, v251, v251
	ds_write_b16 v250, v251 offset:6592
	v_mul_f32_e32 v251, v46, v14
	v_cvt_pk_bf16_f32 v251, v251, v251
	ds_write_b16 v250, v251 offset:6656
	v_mul_f32_e32 v251, v62, v14
	v_cvt_pk_bf16_f32 v251, v251, v251
	ds_write_b16 v250, v251 offset:6720
	v_mul_f32_e32 v251, v78, v14
	v_cvt_pk_bf16_f32 v251, v251, v251
	ds_write_b16 v250, v251 offset:6784
	v_mul_f32_e32 v251, v94, v14
	v_cvt_pk_bf16_f32 v251, v251, v251
	ds_write_b16 v250, v251 offset:6848
	v_mul_f32_e32 v251, v47, v15
	v_cvt_pk_bf16_f32 v251, v251, v251
	ds_write_b16 v250, v251 offset:6912
	v_mul_f32_e32 v251, v63, v15
	v_cvt_pk_bf16_f32 v251, v251, v251
	ds_write_b16 v250, v251 offset:6976
	v_mul_f32_e32 v251, v79, v15
	v_cvt_pk_bf16_f32 v251, v251, v251
	ds_write_b16 v250, v251 offset:7040
	v_mul_f32_e32 v251, v95, v15
	v_cvt_pk_bf16_f32 v251, v251, v251
	ds_write_b16 v250, v251 offset:7104
	s_waitcnt lgkmcnt(0)
	v_lshrrev_b32_e32 v251, 4, v237
	v_and_b32_e32 v244, 15, v237
	v_lshlrev_b32_e32 v245, 8, v251
	v_lshl_or_b32 v245, v244, 4, v245
	v_add_u32_e32 v245, s60, v245
	v_lshlrev_b32_e32 v246, 11, v251
	v_lshl_or_b32 v246, v244, 4, v246
	ds_read_b128 v[16:19], v245 offset:0
	s_waitcnt lgkmcnt(0)
	global_store_dwordx4 v246, v[16:19], s[52:53]
	v_add_u32_e32 v246, 0x2000, v246
	s_nop 1
	ds_read_b128 v[16:19], v245 offset:1024
	s_waitcnt lgkmcnt(0)
	global_store_dwordx4 v246, v[16:19], s[52:53]
	v_add_u32_e32 v246, 0x2000, v246
	s_nop 1
	ds_read_b128 v[16:19], v245 offset:2048
	s_waitcnt lgkmcnt(0)
	global_store_dwordx4 v246, v[16:19], s[52:53]
	v_add_u32_e32 v246, 0x2000, v246
	s_nop 1
	ds_read_b128 v[16:19], v245 offset:3072
	s_waitcnt lgkmcnt(0)
	global_store_dwordx4 v246, v[16:19], s[52:53]
	v_add_u32_e32 v246, 0x2000, v246
	s_nop 1
	ds_read_b128 v[16:19], v245 offset:4096
	s_waitcnt lgkmcnt(0)
	global_store_dwordx4 v246, v[16:19], s[52:53]
	v_add_u32_e32 v246, 0x2000, v246
	s_nop 1
	ds_read_b128 v[16:19], v245 offset:5120
	s_waitcnt lgkmcnt(0)
	global_store_dwordx4 v246, v[16:19], s[52:53]
	v_add_u32_e32 v246, 0x2000, v246
	s_nop 1
	ds_read_b128 v[16:19], v245 offset:6144
	s_waitcnt lgkmcnt(0)
	global_store_dwordx4 v246, v[16:19], s[52:53]
	v_add_u32_e32 v246, 0x2000, v246
	s_nop 1
	ds_read_b128 v[16:19], v245 offset:7168
	s_waitcnt lgkmcnt(0)
	global_store_dwordx4 v246, v[16:19], s[52:53]
	v_add_u32_e32 v246, 0x2000, v246
	s_nop 1
	s_waitcnt lgkmcnt(0)
	s_barrier
